# packed f32 VALU ops split into scalar pairs in the neighbourhood-attention steps and the rope epilogue (guide 7.5)
# speedup vs baseline: 1.0110x; 1.0110x over previous
.LBB0_327:
	v_lshlrev_b32_e32 v74, 4, v237
	s_waitcnt lgkmcnt(14)
	v_mfma_f32_32x32x16_bf16 v[2:17], v[126:129], v[2:5], 0
	v_exp_f32_e32 v76, v76
	v_exp_f32_e32 v77, v77
	v_exp_f32_e32 v78, v78
	v_exp_f32_e32 v79, v79
	s_waitcnt lgkmcnt(12)
	v_mfma_f32_32x32x16_bf16 v[18:33], v[126:129], v[18:21], 0
	v_exp_f32_e32 v80, v80
	v_exp_f32_e32 v81, v81
	v_exp_f32_e32 v82, v82
	v_exp_f32_e32 v83, v83
	v_add_u32_e32 v75, s57, v244
	ds_read_b128 v[150:153], v75
	ds_read_b128 v[146:149], v75 offset:512
	s_waitcnt lgkmcnt(12)
	v_mfma_f32_32x32x16_bf16 v[2:17], v[122:125], v[104:107], v[2:17]
	v_exp_f32_e32 v84, v84
	v_exp_f32_e32 v85, v85
	v_exp_f32_e32 v86, v86
	v_exp_f32_e32 v87, v87
	ds_read_b128 v[178:181], v75 offset:2048
	ds_read_b128 v[170:173], v75 offset:2560
	s_waitcnt lgkmcnt(12)
	v_mfma_f32_32x32x16_bf16 v[18:33], v[122:125], v[100:103], v[18:33]
	v_exp_f32_e32 v88, v88
	v_exp_f32_e32 v89, v89
	v_exp_f32_e32 v90, v90
	v_exp_f32_e32 v91, v91
	ds_read_b128 v[174:177], v75 offset:4096
	ds_read_b128 v[162:165], v75 offset:4608
	s_waitcnt lgkmcnt(12)
	v_mfma_f32_32x32x16_bf16 v[2:17], v[118:121], v[96:99], v[2:17]
	v_exp_f32_e32 v50, v50
	v_exp_f32_e32 v51, v51
	v_exp_f32_e32 v52, v52
	v_exp_f32_e32 v53, v53
	ds_read_b128 v[166:169], v75 offset:6144
	ds_read_b128 v[158:161], v75 offset:6656
	s_waitcnt lgkmcnt(12)
	v_mfma_f32_32x32x16_bf16 v[18:33], v[118:121], v[92:95], v[18:33]
	v_exp_f32_e32 v54, v54
	v_exp_f32_e32 v55, v55
	v_exp_f32_e32 v56, v56
	v_exp_f32_e32 v57, v57
	s_waitcnt lgkmcnt(10)
	v_mfma_f32_32x32x16_bf16 v[2:17], v[114:117], v[70:73], v[2:17]
	v_exp_f32_e32 v58, v58
	v_exp_f32_e32 v59, v59
	v_exp_f32_e32 v60, v60
	v_exp_f32_e32 v61, v61
	s_waitcnt lgkmcnt(8)
	v_mfma_f32_32x32x16_bf16 v[18:33], v[114:117], v[66:69], v[18:33]
	v_exp_f32_e32 v62, v62
	v_exp_f32_e32 v63, v63
	v_exp_f32_e32 v64, v64
	v_exp_f32_e32 v65, v65
	s_waitcnt vmcnt(2) lgkmcnt(0)
	s_barrier
	s_andn2_b64 vcc, exec, s[62:63]
	v_add_u32_e32 v242, s67, v74
	s_cbranch_vccnz .LBB0_329
	s_waitcnt lgkmcnt(0)
	ds_read_b128 v[66:69], v242 offset:96
	ds_read_b128 v[70:73], v242 offset:64
	ds_read_b128 v[92:95], v242 offset:32
	ds_read_b128 v[96:99], v242
	s_waitcnt lgkmcnt(3)
	v_mul_f32_e32 v14, v14, v66
	v_mul_f32_e32 v15, v15, v67
	s_waitcnt lgkmcnt(2)
	v_mul_f32_e32 v10, v10, v70
	v_mul_f32_e32 v11, v11, v71
	s_waitcnt lgkmcnt(1)
	v_mul_f32_e32 v6, v6, v92
	v_mul_f32_e32 v7, v7, v93
	v_mul_f32_e32 v16, v16, v68
	v_mul_f32_e32 v17, v17, v69
	v_mul_f32_e32 v12, v12, v72
	v_mul_f32_e32 v13, v13, v73
	v_mul_f32_e32 v8, v8, v94
	v_mul_f32_e32 v9, v9, v95
	s_waitcnt lgkmcnt(0)
	v_mul_f32_e32 v4, v4, v98
	v_mul_f32_e32 v5, v5, v99
	v_mul_f32_e32 v2, v2, v96
	v_mul_f32_e32 v3, v3, v97
	v_mul_f32_e32 v30, v30, v66
	v_mul_f32_e32 v31, v31, v67
	v_mul_f32_e32 v26, v26, v70
	v_mul_f32_e32 v27, v27, v71
	v_mul_f32_e32 v22, v22, v92
	v_mul_f32_e32 v23, v23, v93
	v_mul_f32_e32 v32, v32, v68
	v_mul_f32_e32 v33, v33, v69
	v_mul_f32_e32 v28, v28, v72
	v_mul_f32_e32 v29, v29, v73
	v_mul_f32_e32 v24, v24, v94
	v_mul_f32_e32 v25, v25, v95
	v_mul_f32_e32 v20, v20, v98
	v_mul_f32_e32 v21, v21, v99
	v_mul_f32_e32 v18, v18, v96
	v_mul_f32_e32 v19, v19, v97

.LBB0_330:
	s_waitcnt lgkmcnt(14)
	v_mfma_f32_32x32x16_bf16 v[2:17], v[126:129], v[154:157], v[2:17]
	v_exp_f32_e32 v98, v98
	v_exp_f32_e32 v99, v99
	v_exp_f32_e32 v100, v100
	v_exp_f32_e32 v101, v101
	s_waitcnt lgkmcnt(12)
	v_mfma_f32_32x32x16_bf16 v[18:33], v[126:129], v[150:153], v[18:33]
	v_exp_f32_e32 v102, v102
	v_exp_f32_e32 v103, v103
	v_exp_f32_e32 v104, v104
	v_exp_f32_e32 v105, v105
	v_add_u32_e32 v62, s67, v244
	ds_read_b128 v[58:61], v62
	ds_read_b128 v[162:165], v62 offset:512
	s_waitcnt lgkmcnt(12)
	v_mfma_f32_32x32x16_bf16 v[2:17], v[122:125], v[146:149], v[2:17]
	v_exp_f32_e32 v106, v106
	v_exp_f32_e32 v107, v107
	v_exp_f32_e32 v108, v108
	v_exp_f32_e32 v109, v109
	ds_read_b128 v[178:181], v62 offset:2048
	ds_read_b128 v[158:161], v62 offset:2560
	s_waitcnt lgkmcnt(12)
	v_mfma_f32_32x32x16_bf16 v[18:33], v[122:125], v[92:95], v[18:33]
	v_exp_f32_e32 v110, v110
	v_exp_f32_e32 v111, v111
	v_exp_f32_e32 v112, v112
	v_exp_f32_e32 v113, v113
	ds_read_b128 v[174:177], v62 offset:4096
	ds_read_b128 v[150:153], v62 offset:4608
	s_waitcnt lgkmcnt(12)
	v_mfma_f32_32x32x16_bf16 v[2:17], v[118:121], v[86:89], v[2:17]
	v_exp_f32_e32 v66, v66
	v_exp_f32_e32 v67, v67
	v_exp_f32_e32 v68, v68
	v_exp_f32_e32 v69, v69
	ds_read_b128 v[154:157], v62 offset:6144
	ds_read_b128 v[146:149], v62 offset:6656
	s_waitcnt lgkmcnt(12)
	v_mfma_f32_32x32x16_bf16 v[18:33], v[118:121], v[82:85], v[18:33]
	v_exp_f32_e32 v70, v70
	v_exp_f32_e32 v71, v71
	v_exp_f32_e32 v72, v72
	v_exp_f32_e32 v73, v73
	s_waitcnt lgkmcnt(10)
	v_mfma_f32_32x32x16_bf16 v[2:17], v[114:117], v[54:57], v[2:17]
	v_exp_f32_e32 v74, v74
	v_exp_f32_e32 v75, v75
	v_exp_f32_e32 v76, v76
	v_exp_f32_e32 v77, v77
	s_waitcnt lgkmcnt(8)
	v_mfma_f32_32x32x16_bf16 v[18:33], v[114:117], v[50:53], v[18:33]
	v_exp_f32_e32 v78, v78
	v_exp_f32_e32 v79, v79
	v_exp_f32_e32 v80, v80
	v_exp_f32_e32 v81, v81
	s_waitcnt vmcnt(2) lgkmcnt(0)
	s_barrier
	s_andn2_b64 vcc, exec, s[62:63]
	s_cbranch_vccnz .LBB0_332
	s_waitcnt lgkmcnt(0)
	ds_read_b128 v[50:53], v242 offset:96
	ds_read_b128 v[54:57], v242 offset:64
	ds_read_b128 v[62:65], v242 offset:32
	ds_read_b128 v[82:85], v242
	s_waitcnt lgkmcnt(3)
	v_mul_f32_e32 v14, v14, v50
	v_mul_f32_e32 v15, v15, v51
	s_waitcnt lgkmcnt(2)
	v_mul_f32_e32 v10, v10, v54
	v_mul_f32_e32 v11, v11, v55
	s_waitcnt lgkmcnt(1)
	v_mul_f32_e32 v6, v6, v62
	v_mul_f32_e32 v7, v7, v63
	v_mul_f32_e32 v16, v16, v52
	v_mul_f32_e32 v17, v17, v53
	v_mul_f32_e32 v12, v12, v56
	v_mul_f32_e32 v13, v13, v57
	v_mul_f32_e32 v8, v8, v64
	v_mul_f32_e32 v9, v9, v65
	s_waitcnt lgkmcnt(0)
	v_mul_f32_e32 v4, v4, v84
	v_mul_f32_e32 v5, v5, v85
	v_mul_f32_e32 v2, v2, v82
	v_mul_f32_e32 v3, v3, v83
	v_mul_f32_e32 v30, v30, v50
	v_mul_f32_e32 v31, v31, v51
	v_mul_f32_e32 v26, v26, v54
	v_mul_f32_e32 v27, v27, v55
	v_mul_f32_e32 v22, v22, v62
	v_mul_f32_e32 v23, v23, v63
	v_mul_f32_e32 v32, v32, v52
	v_mul_f32_e32 v33, v33, v53
	v_mul_f32_e32 v28, v28, v56
	v_mul_f32_e32 v29, v29, v57
	v_mul_f32_e32 v24, v24, v64
	v_mul_f32_e32 v25, v25, v65
	v_mul_f32_e32 v20, v20, v84
	v_mul_f32_e32 v21, v21, v85
	v_mul_f32_e32 v18, v18, v82
	v_mul_f32_e32 v19, v19, v83

.LBB0_335:
	s_waitcnt lgkmcnt(14)
	v_mfma_f32_32x32x16_bf16 v[2:17], v[126:129], v[170:173], v[2:17]
	v_exp_f32_e32 v82, v82
	v_exp_f32_e32 v83, v83
	v_exp_f32_e32 v84, v84
	v_exp_f32_e32 v85, v85
	s_waitcnt lgkmcnt(12)
	v_mfma_f32_32x32x16_bf16 v[18:33], v[126:129], v[166:169], v[18:33]
	v_exp_f32_e32 v86, v86
	v_exp_f32_e32 v87, v87
	v_exp_f32_e32 v88, v88
	v_exp_f32_e32 v89, v89
	v_add_u32_e32 v74, s86, v244
	ds_read_b128 v[110:113], v74
	ds_read_b128 v[166:169], v74 offset:512
	s_waitcnt lgkmcnt(12)
	v_mfma_f32_32x32x16_bf16 v[2:17], v[122:125], v[162:165], v[2:17]
	v_exp_f32_e32 v90, v90
	v_exp_f32_e32 v91, v91
	v_exp_f32_e32 v92, v92
	v_exp_f32_e32 v93, v93
	ds_read_b128 v[162:165], v74 offset:2048
	ds_read_b128 v[194:197], v74 offset:2560
	s_waitcnt lgkmcnt(12)
	v_mfma_f32_32x32x16_bf16 v[18:33], v[122:125], v[106:109], v[18:33]
	v_exp_f32_e32 v94, v94
	v_exp_f32_e32 v95, v95
	v_exp_f32_e32 v96, v96
	v_exp_f32_e32 v97, v97
	ds_read_b128 v[190:193], v74 offset:4096
	ds_read_b128 v[186:189], v74 offset:4608
	s_waitcnt lgkmcnt(12)
	v_mfma_f32_32x32x16_bf16 v[2:17], v[118:121], v[102:105], v[2:17]
	v_exp_f32_e32 v50, v50
	v_exp_f32_e32 v51, v51
	v_exp_f32_e32 v52, v52
	v_exp_f32_e32 v53, v53
	ds_read_b128 v[182:185], v74 offset:6144
	ds_read_b128 v[178:181], v74 offset:6656
	s_waitcnt lgkmcnt(12)
	v_mfma_f32_32x32x16_bf16 v[18:33], v[118:121], v[98:101], v[18:33]
	v_exp_f32_e32 v54, v54
	v_exp_f32_e32 v55, v55
	v_exp_f32_e32 v56, v56
	v_exp_f32_e32 v57, v57
	s_waitcnt lgkmcnt(10)
	v_mfma_f32_32x32x16_bf16 v[2:17], v[114:117], v[70:73], v[2:17]
	v_exp_f32_e32 v58, v58
	v_exp_f32_e32 v59, v59
	v_exp_f32_e32 v60, v60
	v_exp_f32_e32 v61, v61
	s_waitcnt lgkmcnt(8)
	v_mfma_f32_32x32x16_bf16 v[18:33], v[114:117], v[66:69], v[18:33]
	v_exp_f32_e32 v62, v62
	v_exp_f32_e32 v63, v63
	v_exp_f32_e32 v64, v64
	v_exp_f32_e32 v65, v65
	s_waitcnt vmcnt(2) lgkmcnt(0)
	s_barrier
	s_andn2_b64 vcc, exec, s[66:67]
	s_cbranch_vccnz .LBB0_337
	s_waitcnt lgkmcnt(0)
	ds_read_b128 v[66:69], v242 offset:96
	ds_read_b128 v[70:73], v242 offset:64
	ds_read_b128 v[74:77], v242 offset:32
	ds_read_b128 v[78:81], v242
	s_waitcnt lgkmcnt(3)
	v_mul_f32_e32 v16, v16, v68
	v_mul_f32_e32 v17, v17, v69
	s_waitcnt lgkmcnt(2)
	v_mul_f32_e32 v12, v12, v72
	v_mul_f32_e32 v13, v13, v73
	s_waitcnt lgkmcnt(1)
	v_mul_f32_e32 v8, v8, v76
	v_mul_f32_e32 v9, v9, v77
	s_waitcnt lgkmcnt(0)
	v_mul_f32_e32 v4, v4, v80
	v_mul_f32_e32 v5, v5, v81
	v_mul_f32_e32 v14, v14, v66
	v_mul_f32_e32 v15, v15, v67
	v_mul_f32_e32 v10, v10, v70
	v_mul_f32_e32 v11, v11, v71
	v_mul_f32_e32 v6, v6, v74
	v_mul_f32_e32 v7, v7, v75
	v_mul_f32_e32 v2, v2, v78
	v_mul_f32_e32 v3, v3, v79
	v_mul_f32_e32 v32, v32, v68
	v_mul_f32_e32 v33, v33, v69
	v_mul_f32_e32 v28, v28, v72
	v_mul_f32_e32 v29, v29, v73
	v_mul_f32_e32 v24, v24, v76
	v_mul_f32_e32 v25, v25, v77
	v_mul_f32_e32 v20, v20, v80
	v_mul_f32_e32 v21, v21, v81
	v_mul_f32_e32 v30, v30, v66
	v_mul_f32_e32 v31, v31, v67
	v_mul_f32_e32 v26, v26, v70
	v_mul_f32_e32 v27, v27, v71
	v_mul_f32_e32 v22, v22, v74
	v_mul_f32_e32 v23, v23, v75
	v_mul_f32_e32 v18, v18, v78
	v_mul_f32_e32 v19, v19, v79

; __device__ __forceinline__ void na_apply(f32x16&p0,f32x16&p1,const u32x4_t*mf,bool ok){
;   if(!ok){ const float NEG=-INFINITY;
;     #pragma unroll
;     for(int rr=0;rr<16;++rr){p0[rr]=NEG;p1[rr]=NEG;}
;     return; }
;   #pragma unroll
;   for(int rr=0;rr<16;++rr){ const unsigned w0=mf[rr>>3][(rr>>1)&3], w1=mf[2+(rr>>3)][(rr>>1)&3];
;     p0[rr]+=__builtin_bit_cast(float,(rr&1)?(w0&0xffff0000u):(w0<<16)); p1[rr]+=__builtin_bit_cast(float,(rr&1)?(w1&0xffff0000u):(w1<<16)); }
; }
.LBB0_339:
	s_andn2_b64 vcc, exec, s[64:65]
	s_cbranch_vccnz .LBB0_341
	s_waitcnt vmcnt(0)
	v_lshlrev_b32_e32 v50, 16, v158
	v_and_b32_e32 v51, 0xffff0000, v158
	v_add_f32_e32 v66, v66, v50
	v_add_f32_e32 v67, v67, v51
	v_lshlrev_b32_e32 v50, 16, v154
	v_and_b32_e32 v51, 0xffff0000, v154
	v_lshlrev_b32_e32 v52, 16, v159
	v_and_b32_e32 v53, 0xffff0000, v159
	v_lshlrev_b32_e32 v54, 16, v160
	v_and_b32_e32 v55, 0xffff0000, v160
	v_lshlrev_b32_e32 v56, 16, v161
	v_and_b32_e32 v57, 0xffff0000, v161
	v_lshlrev_b32_e32 v58, 16, v150
	v_and_b32_e32 v59, 0xffff0000, v150
	v_lshlrev_b32_e32 v60, 16, v151
	v_and_b32_e32 v61, 0xffff0000, v151
	v_lshlrev_b32_e32 v62, 16, v152
	v_and_b32_e32 v63, 0xffff0000, v152
	v_add_f32_e32 v50, v98, v50
	v_add_f32_e32 v51, v99, v51
	v_add_f32_e32 v68, v68, v52
	v_add_f32_e32 v69, v69, v53
	v_lshlrev_b32_e32 v52, 16, v155
	v_and_b32_e32 v53, 0xffff0000, v155
	v_add_f32_e32 v70, v70, v54
	v_add_f32_e32 v71, v71, v55
	v_lshlrev_b32_e32 v54, 16, v156
	v_and_b32_e32 v55, 0xffff0000, v156
	v_add_f32_e32 v72, v72, v56
	v_add_f32_e32 v73, v73, v57
	v_lshlrev_b32_e32 v56, 16, v157
	v_and_b32_e32 v57, 0xffff0000, v157
	v_add_f32_e32 v74, v74, v58
	v_add_f32_e32 v75, v75, v59
	v_lshlrev_b32_e32 v58, 16, v146
	v_and_b32_e32 v59, 0xffff0000, v146
	v_add_f32_e32 v76, v76, v60
	v_add_f32_e32 v77, v77, v61
	v_lshlrev_b32_e32 v60, 16, v147
	v_and_b32_e32 v61, 0xffff0000, v147
	v_add_f32_e32 v78, v78, v62
	v_add_f32_e32 v79, v79, v63
	v_lshlrev_b32_e32 v62, 16, v148
	v_and_b32_e32 v63, 0xffff0000, v148
	v_lshlrev_b32_e32 v64, 16, v149
	v_lshlrev_b32_e32 v98, 16, v153
	v_and_b32_e32 v99, 0xffff0000, v153
	v_and_b32_e32 v65, 0xffff0000, v149
	v_add_f32_e32 v52, v100, v52
	v_add_f32_e32 v53, v101, v53
	v_add_f32_e32 v54, v102, v54
	v_add_f32_e32 v55, v103, v55
	v_add_f32_e32 v56, v104, v56
	v_add_f32_e32 v57, v105, v57
	v_add_f32_e32 v58, v106, v58
	v_add_f32_e32 v59, v107, v59
	v_add_f32_e32 v60, v108, v60
	v_add_f32_e32 v61, v109, v61
	v_add_f32_e32 v62, v110, v62
	v_add_f32_e32 v63, v111, v63
	v_add_f32_e32 v64, v112, v64
	v_add_f32_e32 v80, v80, v98
	v_add_f32_e32 v81, v81, v99
	v_add_f32_e32 v65, v113, v65
	s_branch .LBB0_342

.LBB0_345:
	s_waitcnt lgkmcnt(14)
	v_mfma_f32_32x32x16_bf16 v[2:17], v[126:129], v[174:177], v[2:17]
	v_exp_f32_e32 v66, v66
	v_exp_f32_e32 v67, v67
	v_exp_f32_e32 v68, v68
	v_exp_f32_e32 v69, v69
	s_waitcnt lgkmcnt(12)
	v_mfma_f32_32x32x16_bf16 v[18:33], v[126:129], v[170:173], v[18:33]
	v_exp_f32_e32 v70, v70
	v_exp_f32_e32 v71, v71
	v_exp_f32_e32 v72, v72
	v_exp_f32_e32 v73, v73
	v_add_u32_e32 v102, s15, v244
	ds_read_b128 v[98:101], v102
	ds_read_b128 v[182:185], v102 offset:512
	s_waitcnt lgkmcnt(12)
	v_mfma_f32_32x32x16_bf16 v[2:17], v[122:125], v[166:169], v[2:17]
	v_exp_f32_e32 v74, v74
	v_exp_f32_e32 v75, v75
	v_exp_f32_e32 v76, v76
	v_exp_f32_e32 v77, v77
	ds_read_b128 v[186:189], v102 offset:2048
	ds_read_b128 v[174:177], v102 offset:2560
	s_waitcnt lgkmcnt(12)
	v_mfma_f32_32x32x16_bf16 v[18:33], v[122:125], v[162:165], v[18:33]
	v_exp_f32_e32 v78, v78
	v_exp_f32_e32 v79, v79
	v_exp_f32_e32 v80, v80
	v_exp_f32_e32 v81, v81
	ds_read_b128 v[178:181], v102 offset:4096
	ds_read_b128 v[166:169], v102 offset:4608
	s_waitcnt lgkmcnt(12)
	v_mfma_f32_32x32x16_bf16 v[2:17], v[118:121], v[86:89], v[2:17]
	v_exp_f32_e32 v50, v50
	v_exp_f32_e32 v51, v51
	v_exp_f32_e32 v52, v52
	v_exp_f32_e32 v53, v53
	ds_read_b128 v[170:173], v102 offset:6144
	ds_read_b128 v[162:165], v102 offset:6656
	s_waitcnt lgkmcnt(12)
	v_mfma_f32_32x32x16_bf16 v[18:33], v[118:121], v[82:85], v[18:33]
	v_exp_f32_e32 v54, v54
	v_exp_f32_e32 v55, v55
	v_exp_f32_e32 v56, v56
	v_exp_f32_e32 v57, v57
	s_waitcnt lgkmcnt(10)
	v_mfma_f32_32x32x16_bf16 v[2:17], v[114:117], v[90:93], v[2:17]
	v_exp_f32_e32 v58, v58
	v_exp_f32_e32 v59, v59
	v_exp_f32_e32 v60, v60
	v_exp_f32_e32 v61, v61
	s_waitcnt lgkmcnt(8)
	v_mfma_f32_32x32x16_bf16 v[18:33], v[114:117], v[94:97], v[18:33]
	v_exp_f32_e32 v62, v62
	v_exp_f32_e32 v63, v63
	v_exp_f32_e32 v64, v64
	v_exp_f32_e32 v65, v65
	s_waitcnt vmcnt(2) lgkmcnt(0)
	s_barrier
	s_andn2_b64 vcc, exec, s[64:65]
	s_cbranch_vccnz .LBB0_347
	s_waitcnt lgkmcnt(0)
	ds_read_b128 v[82:85], v242 offset:96
	ds_read_b128 v[86:89], v242 offset:64
	ds_read_b128 v[90:93], v242 offset:32
	ds_read_b128 v[94:97], v242
	s_waitcnt lgkmcnt(3)
	v_mul_f32_e32 v16, v16, v84
	v_mul_f32_e32 v17, v17, v85
	s_waitcnt lgkmcnt(2)
	v_mul_f32_e32 v12, v12, v88
	v_mul_f32_e32 v13, v13, v89
	s_waitcnt lgkmcnt(1)
	v_mul_f32_e32 v8, v8, v92
	v_mul_f32_e32 v9, v9, v93
	s_waitcnt lgkmcnt(0)
	v_mul_f32_e32 v4, v4, v96
	v_mul_f32_e32 v5, v5, v97
	v_mul_f32_e32 v14, v14, v82
	v_mul_f32_e32 v15, v15, v83
	v_mul_f32_e32 v10, v10, v86
	v_mul_f32_e32 v11, v11, v87
	v_mul_f32_e32 v6, v6, v90
	v_mul_f32_e32 v7, v7, v91
	v_mul_f32_e32 v2, v2, v94
	v_mul_f32_e32 v3, v3, v95
	v_mul_f32_e32 v32, v32, v84
	v_mul_f32_e32 v33, v33, v85
	v_mul_f32_e32 v28, v28, v88
	v_mul_f32_e32 v29, v29, v89
	v_mul_f32_e32 v24, v24, v92
	v_mul_f32_e32 v25, v25, v93
	v_mul_f32_e32 v20, v20, v96
	v_mul_f32_e32 v21, v21, v97
	v_mul_f32_e32 v30, v30, v82
	v_mul_f32_e32 v31, v31, v83
	v_mul_f32_e32 v26, v26, v86
	v_mul_f32_e32 v27, v27, v87
	v_mul_f32_e32 v22, v22, v90
	v_mul_f32_e32 v23, v23, v91
	v_mul_f32_e32 v18, v18, v94
	v_mul_f32_e32 v19, v19, v95

; __device__ __forceinline__ void na_apply(f32x16&p0,f32x16&p1,const u32x4_t*mf,bool ok){
;   if(!ok){ const float NEG=-INFINITY;
;     #pragma unroll
;     for(int rr=0;rr<16;++rr){p0[rr]=NEG;p1[rr]=NEG;}
;     return; }
;   #pragma unroll
;   for(int rr=0;rr<16;++rr){ const unsigned w0=mf[rr>>3][(rr>>1)&3], w1=mf[2+(rr>>3)][(rr>>1)&3];
;     p0[rr]+=__builtin_bit_cast(float,(rr&1)?(w0&0xffff0000u):(w0<<16)); p1[rr]+=__builtin_bit_cast(float,(rr&1)?(w1&0xffff0000u):(w1<<16)); }
; }
.LBB0_350:
	s_andn2_b64 vcc, exec, s[66:67]
	s_cbranch_vccnz .LBB0_352
	s_waitcnt vmcnt(0)
	v_lshlrev_b32_e32 v50, 16, v158
	v_and_b32_e32 v51, 0xffff0000, v158
	v_lshlrev_b32_e32 v52, 16, v159
	v_and_b32_e32 v53, 0xffff0000, v159
	v_lshlrev_b32_e32 v54, 16, v160
	v_and_b32_e32 v55, 0xffff0000, v160
	v_lshlrev_b32_e32 v56, 16, v161
	v_and_b32_e32 v57, 0xffff0000, v161
	v_lshlrev_b32_e32 v58, 16, v150
	v_and_b32_e32 v59, 0xffff0000, v150
	v_lshlrev_b32_e32 v60, 16, v151
	v_and_b32_e32 v61, 0xffff0000, v151
	v_lshlrev_b32_e32 v62, 16, v152
	v_and_b32_e32 v63, 0xffff0000, v152
	v_add_f32_e32 v66, v82, v50
	v_add_f32_e32 v67, v83, v51
	v_lshlrev_b32_e32 v50, 16, v154
	v_and_b32_e32 v51, 0xffff0000, v154
	v_add_f32_e32 v68, v84, v52
	v_add_f32_e32 v69, v85, v53
	v_lshlrev_b32_e32 v52, 16, v155
	v_and_b32_e32 v53, 0xffff0000, v155
	v_add_f32_e32 v70, v86, v54
	v_add_f32_e32 v71, v87, v55
	v_lshlrev_b32_e32 v54, 16, v156
	v_and_b32_e32 v55, 0xffff0000, v156
	v_add_f32_e32 v72, v88, v56
	v_add_f32_e32 v73, v89, v57
	v_lshlrev_b32_e32 v56, 16, v157
	v_and_b32_e32 v57, 0xffff0000, v157
	v_add_f32_e32 v74, v90, v58
	v_add_f32_e32 v75, v91, v59
	v_lshlrev_b32_e32 v58, 16, v146
	v_and_b32_e32 v59, 0xffff0000, v146
	v_add_f32_e32 v76, v92, v60
	v_add_f32_e32 v77, v93, v61
	v_lshlrev_b32_e32 v60, 16, v147
	v_and_b32_e32 v61, 0xffff0000, v147
	v_add_f32_e32 v78, v94, v62
	v_add_f32_e32 v79, v95, v63
	v_lshlrev_b32_e32 v62, 16, v148
	v_and_b32_e32 v63, 0xffff0000, v148
	v_lshlrev_b32_e32 v64, 16, v149
	v_lshlrev_b32_e32 v80, 16, v153
	v_and_b32_e32 v81, 0xffff0000, v153
	v_and_b32_e32 v65, 0xffff0000, v149
	v_add_f32_e32 v50, v98, v50
	v_add_f32_e32 v51, v99, v51
	v_add_f32_e32 v52, v100, v52
	v_add_f32_e32 v53, v101, v53
	v_add_f32_e32 v54, v102, v54
	v_add_f32_e32 v55, v103, v55
	v_add_f32_e32 v56, v104, v56
	v_add_f32_e32 v57, v105, v57
	v_add_f32_e32 v58, v106, v58
	v_add_f32_e32 v59, v107, v59
	v_add_f32_e32 v60, v108, v60
	v_add_f32_e32 v61, v109, v61
	v_add_f32_e32 v62, v110, v62
	v_add_f32_e32 v63, v111, v63
	v_add_f32_e32 v64, v112, v64
	v_add_f32_e32 v80, v96, v80
	v_add_f32_e32 v81, v97, v81
	v_add_f32_e32 v65, v113, v65
	s_branch .LBB0_353

.LBB0_356:
	s_waitcnt lgkmcnt(14)
	v_mfma_f32_32x32x16_bf16 v[2:17], v[126:129], v[198:201], v[2:17]
	v_exp_f32_e32 v66, v66
	v_exp_f32_e32 v67, v67
	v_exp_f32_e32 v68, v68
	v_exp_f32_e32 v69, v69
	s_waitcnt lgkmcnt(12)
	v_mfma_f32_32x32x16_bf16 v[18:33], v[126:129], v[194:197], v[18:33]
	v_exp_f32_e32 v70, v70
	v_exp_f32_e32 v71, v71
	v_exp_f32_e32 v72, v72
	v_exp_f32_e32 v73, v73
	v_add_u32_e32 v82, s84, v244
	ds_read_b128 v[98:101], v82
	ds_read_b128 v[162:165], v82 offset:512
	s_waitcnt lgkmcnt(12)
	v_mfma_f32_32x32x16_bf16 v[2:17], v[122:125], v[190:193], v[2:17]
	v_exp_f32_e32 v74, v74
	v_exp_f32_e32 v75, v75
	v_exp_f32_e32 v76, v76
	v_exp_f32_e32 v77, v77
	ds_read_b128 v[198:201], v82 offset:2048
	ds_read_b128 v[194:197], v82 offset:2560
	s_waitcnt lgkmcnt(12)
	v_mfma_f32_32x32x16_bf16 v[18:33], v[122:125], v[182:185], v[18:33]
	v_exp_f32_e32 v78, v78
	v_exp_f32_e32 v79, v79
	v_exp_f32_e32 v80, v80
	v_exp_f32_e32 v81, v81
	ds_read_b128 v[190:193], v82 offset:4096
	ds_read_b128 v[182:185], v82 offset:4608
	s_waitcnt lgkmcnt(12)
	v_mfma_f32_32x32x16_bf16 v[2:17], v[118:121], v[186:189], v[2:17]
	v_exp_f32_e32 v50, v50
	v_exp_f32_e32 v51, v51
	v_exp_f32_e32 v52, v52
	v_exp_f32_e32 v53, v53
	ds_read_b128 v[186:189], v82 offset:6144
	ds_read_b128 v[178:181], v82 offset:6656
	s_waitcnt lgkmcnt(12)
	v_mfma_f32_32x32x16_bf16 v[18:33], v[118:121], v[174:177], v[18:33]
	v_exp_f32_e32 v54, v54
	v_exp_f32_e32 v55, v55
	v_exp_f32_e32 v56, v56
	v_exp_f32_e32 v57, v57
	s_waitcnt lgkmcnt(10)
	v_mfma_f32_32x32x16_bf16 v[2:17], v[114:117], v[166:169], v[2:17]
	v_exp_f32_e32 v58, v58
	v_exp_f32_e32 v59, v59
	v_exp_f32_e32 v60, v60
	v_exp_f32_e32 v61, v61
	s_waitcnt lgkmcnt(8)
	v_mfma_f32_32x32x16_bf16 v[18:33], v[114:117], v[170:173], v[18:33]
	v_exp_f32_e32 v62, v62
	v_exp_f32_e32 v63, v63
	v_exp_f32_e32 v64, v64
	v_exp_f32_e32 v65, v65
	s_waitcnt vmcnt(2) lgkmcnt(0)
	s_barrier
	s_andn2_b64 vcc, exec, s[70:71]
	s_cbranch_vccnz .LBB0_358
	s_waitcnt lgkmcnt(0)
	ds_read_b128 v[82:85], v242 offset:96
	ds_read_b128 v[86:89], v242 offset:64
	ds_read_b128 v[90:93], v242 offset:32
	ds_read_b128 v[94:97], v242
	s_waitcnt lgkmcnt(3)
	v_mul_f32_e32 v16, v16, v84
	v_mul_f32_e32 v17, v17, v85
	s_waitcnt lgkmcnt(2)
	v_mul_f32_e32 v12, v12, v88
	v_mul_f32_e32 v13, v13, v89
	s_waitcnt lgkmcnt(1)
	v_mul_f32_e32 v8, v8, v92
	v_mul_f32_e32 v9, v9, v93
	s_waitcnt lgkmcnt(0)
	v_mul_f32_e32 v4, v4, v96
	v_mul_f32_e32 v5, v5, v97
	v_mul_f32_e32 v14, v14, v82
	v_mul_f32_e32 v15, v15, v83
	v_mul_f32_e32 v10, v10, v86
	v_mul_f32_e32 v11, v11, v87
	v_mul_f32_e32 v6, v6, v90
	v_mul_f32_e32 v7, v7, v91
	v_mul_f32_e32 v2, v2, v94
	v_mul_f32_e32 v3, v3, v95
	v_mul_f32_e32 v32, v32, v84
	v_mul_f32_e32 v33, v33, v85
	v_mul_f32_e32 v28, v28, v88
	v_mul_f32_e32 v29, v29, v89
	v_mul_f32_e32 v24, v24, v92
	v_mul_f32_e32 v25, v25, v93
	v_mul_f32_e32 v20, v20, v96
	v_mul_f32_e32 v21, v21, v97
	v_mul_f32_e32 v30, v30, v82
	v_mul_f32_e32 v31, v31, v83
	v_mul_f32_e32 v26, v26, v86
	v_mul_f32_e32 v27, v27, v87
	v_mul_f32_e32 v22, v22, v90
	v_mul_f32_e32 v23, v23, v91
	v_mul_f32_e32 v18, v18, v94
	v_mul_f32_e32 v19, v19, v95

.LBB0_366:
	s_waitcnt lgkmcnt(14)
	v_mfma_f32_32x32x16_bf16 v[2:17], v[126:129], v[174:177], v[2:17]
	v_exp_f32_e32 v66, v66
	v_exp_f32_e32 v67, v67
	v_exp_f32_e32 v68, v68
	v_exp_f32_e32 v69, v69
	s_waitcnt lgkmcnt(12)
	v_mfma_f32_32x32x16_bf16 v[18:33], v[126:129], v[170:173], v[18:33]
	v_exp_f32_e32 v70, v70
	v_exp_f32_e32 v71, v71
	v_exp_f32_e32 v72, v72
	v_exp_f32_e32 v73, v73
	v_add_u32_e32 v82, s15, v244
	ds_read_b128 v[98:101], v82
	ds_read_b128 v[182:185], v82 offset:512
	s_waitcnt lgkmcnt(12)
	v_mfma_f32_32x32x16_bf16 v[2:17], v[122:125], v[166:169], v[2:17]
	v_exp_f32_e32 v74, v74
	v_exp_f32_e32 v75, v75
	v_exp_f32_e32 v76, v76
	v_exp_f32_e32 v77, v77
	ds_read_b128 v[186:189], v82 offset:2048
	ds_read_b128 v[174:177], v82 offset:2560
	s_waitcnt lgkmcnt(12)
	v_mfma_f32_32x32x16_bf16 v[18:33], v[122:125], v[162:165], v[18:33]
	v_exp_f32_e32 v78, v78
	v_exp_f32_e32 v79, v79
	v_exp_f32_e32 v80, v80
	v_exp_f32_e32 v81, v81
	ds_read_b128 v[178:181], v82 offset:4096
	ds_read_b128 v[166:169], v82 offset:4608
	s_waitcnt lgkmcnt(12)
	v_mfma_f32_32x32x16_bf16 v[2:17], v[118:121], v[202:205], v[2:17]
	v_exp_f32_e32 v50, v50
	v_exp_f32_e32 v51, v51
	v_exp_f32_e32 v52, v52
	v_exp_f32_e32 v53, v53
	ds_read_b128 v[170:173], v82 offset:6144
	ds_read_b128 v[162:165], v82 offset:6656
	s_waitcnt lgkmcnt(12)
	v_mfma_f32_32x32x16_bf16 v[18:33], v[118:121], v[190:193], v[18:33]
	v_exp_f32_e32 v54, v54
	v_exp_f32_e32 v55, v55
	v_exp_f32_e32 v56, v56
	v_exp_f32_e32 v57, v57
	s_waitcnt lgkmcnt(10)
	v_mfma_f32_32x32x16_bf16 v[2:17], v[114:117], v[194:197], v[2:17]
	v_exp_f32_e32 v58, v58
	v_exp_f32_e32 v59, v59
	v_exp_f32_e32 v60, v60
	v_exp_f32_e32 v61, v61
	s_waitcnt lgkmcnt(8)
	v_mfma_f32_32x32x16_bf16 v[18:33], v[114:117], v[198:201], v[18:33]
	v_exp_f32_e32 v62, v62
	v_exp_f32_e32 v63, v63
	v_exp_f32_e32 v64, v64
	v_exp_f32_e32 v65, v65
	s_waitcnt vmcnt(2) lgkmcnt(0)
	s_barrier
	s_andn2_b64 vcc, exec, s[66:67]
	s_cbranch_vccnz .LBB0_368
	s_waitcnt lgkmcnt(0)
	ds_read_b128 v[82:85], v242 offset:96
	ds_read_b128 v[86:89], v242 offset:64
	ds_read_b128 v[90:93], v242 offset:32
	ds_read_b128 v[94:97], v242
	s_waitcnt lgkmcnt(3)
	v_mul_f32_e32 v16, v16, v84
	v_mul_f32_e32 v17, v17, v85
	s_waitcnt lgkmcnt(2)
	v_mul_f32_e32 v12, v12, v88
	v_mul_f32_e32 v13, v13, v89
	s_waitcnt lgkmcnt(1)
	v_mul_f32_e32 v8, v8, v92
	v_mul_f32_e32 v9, v9, v93
	s_waitcnt lgkmcnt(0)
	v_mul_f32_e32 v4, v4, v96
	v_mul_f32_e32 v5, v5, v97
	v_mul_f32_e32 v14, v14, v82
	v_mul_f32_e32 v15, v15, v83
	v_mul_f32_e32 v10, v10, v86
	v_mul_f32_e32 v11, v11, v87
	v_mul_f32_e32 v6, v6, v90
	v_mul_f32_e32 v7, v7, v91
	v_mul_f32_e32 v2, v2, v94
	v_mul_f32_e32 v3, v3, v95
	v_mul_f32_e32 v32, v32, v84
	v_mul_f32_e32 v33, v33, v85
	v_mul_f32_e32 v28, v28, v88
	v_mul_f32_e32 v29, v29, v89
	v_mul_f32_e32 v24, v24, v92
	v_mul_f32_e32 v25, v25, v93
	v_mul_f32_e32 v20, v20, v96
	v_mul_f32_e32 v21, v21, v97
	v_mul_f32_e32 v30, v30, v82
	v_mul_f32_e32 v31, v31, v83
	v_mul_f32_e32 v26, v26, v86
	v_mul_f32_e32 v27, v27, v87
	v_mul_f32_e32 v22, v22, v90
	v_mul_f32_e32 v23, v23, v91
	v_mul_f32_e32 v18, v18, v94
	v_mul_f32_e32 v19, v19, v95

; __device__ __forceinline__ void na_apply(f32x16&p0,f32x16&p1,const u32x4_t*mf,bool ok){
;   if(!ok){ const float NEG=-INFINITY;
;     #pragma unroll
;     for(int rr=0;rr<16;++rr){p0[rr]=NEG;p1[rr]=NEG;}
;     return; }
;   #pragma unroll
;   for(int rr=0;rr<16;++rr){ const unsigned w0=mf[rr>>3][(rr>>1)&3], w1=mf[2+(rr>>3)][(rr>>1)&3];
;     p0[rr]+=__builtin_bit_cast(float,(rr&1)?(w0&0xffff0000u):(w0<<16)); p1[rr]+=__builtin_bit_cast(float,(rr&1)?(w1&0xffff0000u):(w1<<16)); }
; }
.LBB0_378:
	s_andn2_b64 vcc, exec, s[64:65]
	s_cbranch_vccnz .LBB0_380
	s_waitcnt vmcnt(0)
	v_lshlrev_b32_e32 v50, 16, v158
	v_and_b32_e32 v51, 0xffff0000, v158
	v_lshlrev_b32_e32 v52, 16, v159
	v_and_b32_e32 v53, 0xffff0000, v159
	v_lshlrev_b32_e32 v54, 16, v160
	v_and_b32_e32 v55, 0xffff0000, v160
	v_lshlrev_b32_e32 v56, 16, v161
	v_and_b32_e32 v57, 0xffff0000, v161
	v_lshlrev_b32_e32 v58, 16, v150
	v_and_b32_e32 v59, 0xffff0000, v150
	v_lshlrev_b32_e32 v60, 16, v151
	v_and_b32_e32 v61, 0xffff0000, v151
	v_lshlrev_b32_e32 v62, 16, v152
	v_and_b32_e32 v63, 0xffff0000, v152
	v_add_f32_e32 v66, v82, v50
	v_add_f32_e32 v67, v83, v51
	v_lshlrev_b32_e32 v50, 16, v154
	v_and_b32_e32 v51, 0xffff0000, v154
	v_add_f32_e32 v68, v84, v52
	v_add_f32_e32 v69, v85, v53
	v_lshlrev_b32_e32 v52, 16, v155
	v_and_b32_e32 v53, 0xffff0000, v155
	v_add_f32_e32 v70, v86, v54
	v_add_f32_e32 v71, v87, v55
	v_lshlrev_b32_e32 v54, 16, v156
	v_and_b32_e32 v55, 0xffff0000, v156
	v_add_f32_e32 v72, v88, v56
	v_add_f32_e32 v73, v89, v57
	v_lshlrev_b32_e32 v56, 16, v157
	v_and_b32_e32 v57, 0xffff0000, v157
	v_add_f32_e32 v74, v90, v58
	v_add_f32_e32 v75, v91, v59
	v_lshlrev_b32_e32 v58, 16, v146
	v_and_b32_e32 v59, 0xffff0000, v146
	v_add_f32_e32 v76, v92, v60
	v_add_f32_e32 v77, v93, v61
	v_lshlrev_b32_e32 v60, 16, v147
	v_and_b32_e32 v61, 0xffff0000, v147
	v_add_f32_e32 v78, v94, v62
	v_add_f32_e32 v79, v95, v63
	v_lshlrev_b32_e32 v62, 16, v148
	v_and_b32_e32 v63, 0xffff0000, v148
	v_lshlrev_b32_e32 v64, 16, v149
	v_lshlrev_b32_e32 v80, 16, v153
	v_and_b32_e32 v81, 0xffff0000, v153
	v_and_b32_e32 v65, 0xffff0000, v149
	v_add_f32_e32 v50, v98, v50
	v_add_f32_e32 v51, v99, v51
	v_add_f32_e32 v52, v100, v52
	v_add_f32_e32 v53, v101, v53
	v_add_f32_e32 v54, v102, v54
	v_add_f32_e32 v55, v103, v55
	v_add_f32_e32 v56, v104, v56
	v_add_f32_e32 v57, v105, v57
	v_add_f32_e32 v58, v106, v58
	v_add_f32_e32 v59, v107, v59
	v_add_f32_e32 v60, v108, v60
	v_add_f32_e32 v61, v109, v61
	v_add_f32_e32 v62, v110, v62
	v_add_f32_e32 v63, v111, v63
	v_add_f32_e32 v64, v112, v64
	v_add_f32_e32 v80, v96, v80
	v_add_f32_e32 v81, v97, v81
	v_add_f32_e32 v65, v113, v65
	s_branch .LBB0_381

.LBB0_384:
	s_waitcnt lgkmcnt(14)
	v_mfma_f32_32x32x16_bf16 v[2:17], v[126:129], v[198:201], v[2:17]
	v_exp_f32_e32 v66, v66
	v_exp_f32_e32 v67, v67
	v_exp_f32_e32 v68, v68
	v_exp_f32_e32 v69, v69
	s_waitcnt lgkmcnt(12)
	v_mfma_f32_32x32x16_bf16 v[18:33], v[126:129], v[194:197], v[18:33]
	v_exp_f32_e32 v70, v70
	v_exp_f32_e32 v71, v71
	v_exp_f32_e32 v72, v72
	v_exp_f32_e32 v73, v73
	v_add_u32_e32 v82, s73, v244
	ds_read_b128 v[98:101], v82
	ds_read_b128 v[206:209], v82 offset:512
	s_waitcnt lgkmcnt(12)
	v_mfma_f32_32x32x16_bf16 v[2:17], v[122:125], v[190:193], v[2:17]
	v_exp_f32_e32 v74, v74
	v_exp_f32_e32 v75, v75
	v_exp_f32_e32 v76, v76
	v_exp_f32_e32 v77, v77
	ds_read_b128 v[210:213], v82 offset:2048
	ds_read_b128 v[170:173], v82 offset:2560
	s_waitcnt lgkmcnt(12)
	v_mfma_f32_32x32x16_bf16 v[18:33], v[122:125], v[186:189], v[18:33]
	v_exp_f32_e32 v78, v78
	v_exp_f32_e32 v79, v79
	v_exp_f32_e32 v80, v80
	v_exp_f32_e32 v81, v81
	ds_read_b128 v[202:205], v82 offset:4096
	ds_read_b128 v[162:165], v82 offset:4608
	s_waitcnt lgkmcnt(12)
	v_mfma_f32_32x32x16_bf16 v[2:17], v[118:121], v[182:185], v[2:17]
	v_exp_f32_e32 v50, v50
	v_exp_f32_e32 v51, v51
	v_exp_f32_e32 v52, v52
	v_exp_f32_e32 v53, v53
	ds_read_b128 v[198:201], v82 offset:6144
	ds_read_b128 v[194:197], v82 offset:6656
	s_waitcnt lgkmcnt(12)
	v_mfma_f32_32x32x16_bf16 v[18:33], v[118:121], v[178:181], v[18:33]
	v_exp_f32_e32 v54, v54
	v_exp_f32_e32 v55, v55
	v_exp_f32_e32 v56, v56
	v_exp_f32_e32 v57, v57
	s_waitcnt lgkmcnt(10)
	v_mfma_f32_32x32x16_bf16 v[2:17], v[114:117], v[174:177], v[2:17]
	v_exp_f32_e32 v58, v58
	v_exp_f32_e32 v59, v59
	v_exp_f32_e32 v60, v60
	v_exp_f32_e32 v61, v61
	s_waitcnt lgkmcnt(8)
	v_mfma_f32_32x32x16_bf16 v[18:33], v[114:117], v[166:169], v[18:33]
	v_exp_f32_e32 v62, v62
	v_exp_f32_e32 v63, v63
	v_exp_f32_e32 v64, v64
	v_exp_f32_e32 v65, v65
	s_waitcnt vmcnt(2) lgkmcnt(0)
	s_barrier
	s_andn2_b64 vcc, exec, s[66:67]
	s_cbranch_vccnz .LBB0_386
	s_waitcnt lgkmcnt(0)
	ds_read_b128 v[82:85], v242 offset:96
	ds_read_b128 v[86:89], v242 offset:64
	ds_read_b128 v[90:93], v242 offset:32
	ds_read_b128 v[94:97], v242
	s_waitcnt lgkmcnt(3)
	v_mul_f32_e32 v16, v16, v84
	v_mul_f32_e32 v17, v17, v85
	s_waitcnt lgkmcnt(2)
	v_mul_f32_e32 v12, v12, v88
	v_mul_f32_e32 v13, v13, v89
	s_waitcnt lgkmcnt(1)
	v_mul_f32_e32 v8, v8, v92
	v_mul_f32_e32 v9, v9, v93
	s_waitcnt lgkmcnt(0)
	v_mul_f32_e32 v4, v4, v96
	v_mul_f32_e32 v5, v5, v97
	v_mul_f32_e32 v14, v14, v82
	v_mul_f32_e32 v15, v15, v83
	v_mul_f32_e32 v10, v10, v86
	v_mul_f32_e32 v11, v11, v87
	v_mul_f32_e32 v6, v6, v90
	v_mul_f32_e32 v7, v7, v91
	v_mul_f32_e32 v2, v2, v94
	v_mul_f32_e32 v3, v3, v95
	v_mul_f32_e32 v32, v32, v84
	v_mul_f32_e32 v33, v33, v85
	v_mul_f32_e32 v28, v28, v88
	v_mul_f32_e32 v29, v29, v89
	v_mul_f32_e32 v24, v24, v92
	v_mul_f32_e32 v25, v25, v93
	v_mul_f32_e32 v20, v20, v96
	v_mul_f32_e32 v21, v21, v97
	v_mul_f32_e32 v30, v30, v82
	v_mul_f32_e32 v31, v31, v83
	v_mul_f32_e32 v26, v26, v86
	v_mul_f32_e32 v27, v27, v87
	v_mul_f32_e32 v22, v22, v90
	v_mul_f32_e32 v23, v23, v91
	v_mul_f32_e32 v18, v18, v94
	v_mul_f32_e32 v19, v19, v95

.LBB0_394:
	s_waitcnt lgkmcnt(14)
	v_mfma_f32_32x32x16_bf16 v[2:17], v[126:129], v[190:193], v[2:17]
	v_exp_f32_e32 v66, v66
	v_exp_f32_e32 v67, v67
	v_exp_f32_e32 v68, v68
	v_exp_f32_e32 v69, v69
	s_waitcnt lgkmcnt(12)
	v_mfma_f32_32x32x16_bf16 v[18:33], v[126:129], v[186:189], v[18:33]
	v_exp_f32_e32 v70, v70
	v_exp_f32_e32 v71, v71
	v_exp_f32_e32 v72, v72
	v_exp_f32_e32 v73, v73
	v_add_u32_e32 v82, s15, v244
	ds_read_b128 v[98:101], v82
	ds_read_b128 v[214:217], v82 offset:512
	s_waitcnt lgkmcnt(12)
	v_mfma_f32_32x32x16_bf16 v[2:17], v[122:125], v[182:185], v[2:17]
	v_exp_f32_e32 v74, v74
	v_exp_f32_e32 v75, v75
	v_exp_f32_e32 v76, v76
	v_exp_f32_e32 v77, v77
	ds_read_b128 v[218:221], v82 offset:2048
	ds_read_b128 v[206:209], v82 offset:2560
	s_waitcnt lgkmcnt(12)
	v_mfma_f32_32x32x16_bf16 v[18:33], v[122:125], v[178:181], v[18:33]
	v_exp_f32_e32 v78, v78
	v_exp_f32_e32 v79, v79
	v_exp_f32_e32 v80, v80
	v_exp_f32_e32 v81, v81
	ds_read_b128 v[210:213], v82 offset:4096
	ds_read_b128 v[198:201], v82 offset:4608
	s_waitcnt lgkmcnt(12)
	v_mfma_f32_32x32x16_bf16 v[2:17], v[118:121], v[174:177], v[2:17]
	v_exp_f32_e32 v50, v50
	v_exp_f32_e32 v51, v51
	v_exp_f32_e32 v52, v52
	v_exp_f32_e32 v53, v53
	ds_read_b128 v[202:205], v82 offset:6144
	ds_read_b128 v[194:197], v82 offset:6656
	s_waitcnt lgkmcnt(12)
	v_mfma_f32_32x32x16_bf16 v[18:33], v[118:121], v[170:173], v[18:33]
	v_exp_f32_e32 v54, v54
	v_exp_f32_e32 v55, v55
	v_exp_f32_e32 v56, v56
	v_exp_f32_e32 v57, v57
	s_waitcnt lgkmcnt(10)
	v_mfma_f32_32x32x16_bf16 v[2:17], v[114:117], v[166:169], v[2:17]
	v_exp_f32_e32 v58, v58
	v_exp_f32_e32 v59, v59
	v_exp_f32_e32 v60, v60
	v_exp_f32_e32 v61, v61
	s_waitcnt lgkmcnt(8)
	v_mfma_f32_32x32x16_bf16 v[18:33], v[114:117], v[162:165], v[18:33]
	v_exp_f32_e32 v62, v62
	v_exp_f32_e32 v63, v63
	v_exp_f32_e32 v64, v64
	v_exp_f32_e32 v65, v65
	s_waitcnt vmcnt(2) lgkmcnt(0)
	s_barrier
	s_andn2_b64 vcc, exec, s[66:67]
	s_cbranch_vccnz .LBB0_396
	s_waitcnt lgkmcnt(0)
	ds_read_b128 v[82:85], v242 offset:96
	ds_read_b128 v[86:89], v242 offset:64
	ds_read_b128 v[90:93], v242 offset:32
	ds_read_b128 v[94:97], v242
	s_waitcnt lgkmcnt(3)
	v_mul_f32_e32 v16, v16, v84
	v_mul_f32_e32 v17, v17, v85
	s_waitcnt lgkmcnt(2)
	v_mul_f32_e32 v12, v12, v88
	v_mul_f32_e32 v13, v13, v89
	s_waitcnt lgkmcnt(1)
	v_mul_f32_e32 v8, v8, v92
	v_mul_f32_e32 v9, v9, v93
	s_waitcnt lgkmcnt(0)
	v_mul_f32_e32 v4, v4, v96
	v_mul_f32_e32 v5, v5, v97
	v_mul_f32_e32 v14, v14, v82
	v_mul_f32_e32 v15, v15, v83
	v_mul_f32_e32 v10, v10, v86
	v_mul_f32_e32 v11, v11, v87
	v_mul_f32_e32 v6, v6, v90
	v_mul_f32_e32 v7, v7, v91
	v_mul_f32_e32 v2, v2, v94
	v_mul_f32_e32 v3, v3, v95
	v_mul_f32_e32 v32, v32, v84
	v_mul_f32_e32 v33, v33, v85
	v_mul_f32_e32 v28, v28, v88
	v_mul_f32_e32 v29, v29, v89
	v_mul_f32_e32 v24, v24, v92
	v_mul_f32_e32 v25, v25, v93
	v_mul_f32_e32 v20, v20, v96
	v_mul_f32_e32 v21, v21, v97
	v_mul_f32_e32 v30, v30, v82
	v_mul_f32_e32 v31, v31, v83
	v_mul_f32_e32 v26, v26, v86
	v_mul_f32_e32 v27, v27, v87
	v_mul_f32_e32 v22, v22, v90
	v_mul_f32_e32 v23, v23, v91
	v_mul_f32_e32 v18, v18, v94
	v_mul_f32_e32 v19, v19, v95

.LBB0_404:
	s_waitcnt lgkmcnt(14)
	v_mfma_f32_32x32x16_bf16 v[2:17], v[126:129], v[190:193], v[2:17]
	v_exp_f32_e32 v66, v66
	v_exp_f32_e32 v67, v67
	v_exp_f32_e32 v68, v68
	v_exp_f32_e32 v69, v69
	s_waitcnt lgkmcnt(12)
	v_mfma_f32_32x32x16_bf16 v[18:33], v[126:129], v[186:189], v[18:33]
	v_exp_f32_e32 v70, v70
	v_exp_f32_e32 v71, v71
	v_exp_f32_e32 v72, v72
	v_exp_f32_e32 v73, v73
	v_add_u32_e32 v82, s3, v244
	ds_read_b128 v[98:101], v82
	ds_read_b128 v[214:217], v82 offset:512
	s_waitcnt lgkmcnt(12)
	v_mfma_f32_32x32x16_bf16 v[2:17], v[122:125], v[182:185], v[2:17]
	v_exp_f32_e32 v74, v74
	v_exp_f32_e32 v75, v75
	v_exp_f32_e32 v76, v76
	v_exp_f32_e32 v77, v77
	ds_read_b128 v[218:221], v82 offset:2048
	ds_read_b128 v[206:209], v82 offset:2560
	s_waitcnt lgkmcnt(12)
	v_mfma_f32_32x32x16_bf16 v[18:33], v[122:125], v[178:181], v[18:33]
	v_exp_f32_e32 v78, v78
	v_exp_f32_e32 v79, v79
	v_exp_f32_e32 v80, v80
	v_exp_f32_e32 v81, v81
	ds_read_b128 v[210:213], v82 offset:4096
	ds_read_b128 v[198:201], v82 offset:4608
	s_waitcnt lgkmcnt(12)
	v_mfma_f32_32x32x16_bf16 v[2:17], v[118:121], v[174:177], v[2:17]
	v_exp_f32_e32 v50, v50
	v_exp_f32_e32 v51, v51
	v_exp_f32_e32 v52, v52
	v_exp_f32_e32 v53, v53
	ds_read_b128 v[202:205], v82 offset:6144
	ds_read_b128 v[194:197], v82 offset:6656
	s_waitcnt lgkmcnt(12)
	v_mfma_f32_32x32x16_bf16 v[18:33], v[118:121], v[170:173], v[18:33]
	v_exp_f32_e32 v54, v54
	v_exp_f32_e32 v55, v55
	v_exp_f32_e32 v56, v56
	v_exp_f32_e32 v57, v57
	s_waitcnt lgkmcnt(10)
	v_mfma_f32_32x32x16_bf16 v[2:17], v[114:117], v[166:169], v[2:17]
	v_exp_f32_e32 v58, v58
	v_exp_f32_e32 v59, v59
	v_exp_f32_e32 v60, v60
	v_exp_f32_e32 v61, v61
	s_waitcnt lgkmcnt(8)
	v_mfma_f32_32x32x16_bf16 v[18:33], v[114:117], v[162:165], v[18:33]
	v_exp_f32_e32 v62, v62
	v_exp_f32_e32 v63, v63
	v_exp_f32_e32 v64, v64
	v_exp_f32_e32 v65, v65
	s_waitcnt vmcnt(1) lgkmcnt(0)
	s_barrier
	s_andn2_b64 vcc, exec, s[66:67]
	s_cbranch_vccnz .LBB0_406
	s_waitcnt lgkmcnt(0)
	ds_read_b128 v[82:85], v242 offset:96
	ds_read_b128 v[86:89], v242 offset:64
	ds_read_b128 v[90:93], v242 offset:32
	ds_read_b128 v[94:97], v242
	s_waitcnt lgkmcnt(3)
	v_mul_f32_e32 v16, v16, v84
	v_mul_f32_e32 v17, v17, v85
	s_waitcnt lgkmcnt(2)
	v_mul_f32_e32 v12, v12, v88
	v_mul_f32_e32 v13, v13, v89
	s_waitcnt lgkmcnt(1)
	v_mul_f32_e32 v8, v8, v92
	v_mul_f32_e32 v9, v9, v93
	s_waitcnt lgkmcnt(0)
	v_mul_f32_e32 v4, v4, v96
	v_mul_f32_e32 v5, v5, v97
	v_mul_f32_e32 v14, v14, v82
	v_mul_f32_e32 v15, v15, v83
	v_mul_f32_e32 v10, v10, v86
	v_mul_f32_e32 v11, v11, v87
	v_mul_f32_e32 v6, v6, v90
	v_mul_f32_e32 v7, v7, v91
	v_mul_f32_e32 v2, v2, v94
	v_mul_f32_e32 v3, v3, v95
	v_mul_f32_e32 v32, v32, v84
	v_mul_f32_e32 v33, v33, v85
	v_mul_f32_e32 v28, v28, v88
	v_mul_f32_e32 v29, v29, v89
	v_mul_f32_e32 v24, v24, v92
	v_mul_f32_e32 v25, v25, v93
	v_mul_f32_e32 v20, v20, v96
	v_mul_f32_e32 v21, v21, v97
	v_mul_f32_e32 v30, v30, v82
	v_mul_f32_e32 v31, v31, v83
	v_mul_f32_e32 v26, v26, v86
	v_mul_f32_e32 v27, v27, v87
	v_mul_f32_e32 v22, v22, v90
	v_mul_f32_e32 v23, v23, v91
	v_mul_f32_e32 v18, v18, v94
	v_mul_f32_e32 v19, v19, v95

.LBB0_414:
	s_waitcnt lgkmcnt(14)
	v_mfma_f32_32x32x16_bf16 v[2:17], v[126:129], v[190:193], v[2:17]
	v_exp_f32_e32 v66, v66
	v_exp_f32_e32 v67, v67
	v_exp_f32_e32 v68, v68
	v_exp_f32_e32 v69, v69
	s_waitcnt lgkmcnt(12)
	v_mfma_f32_32x32x16_bf16 v[18:33], v[126:129], v[186:189], v[18:33]
	v_exp_f32_e32 v70, v70
	v_exp_f32_e32 v71, v71
	v_exp_f32_e32 v72, v72
	v_exp_f32_e32 v73, v73
	v_add_u32_e32 v82, s13, v244
	ds_read_b128 v[186:189], v82
	ds_read_b128 v[110:113], v82 offset:512
	s_waitcnt lgkmcnt(12)
	v_mfma_f32_32x32x16_bf16 v[2:17], v[122:125], v[182:185], v[2:17]
	v_exp_f32_e32 v74, v74
	v_exp_f32_e32 v75, v75
	v_exp_f32_e32 v76, v76
	v_exp_f32_e32 v77, v77
	ds_read_b128 v[182:185], v82 offset:2048
	ds_read_b128 v[102:105], v82 offset:2560
	s_waitcnt lgkmcnt(12)
	v_mfma_f32_32x32x16_bf16 v[18:33], v[122:125], v[178:181], v[18:33]
	v_exp_f32_e32 v78, v78
	v_exp_f32_e32 v79, v79
	v_exp_f32_e32 v80, v80
	v_exp_f32_e32 v81, v81
	ds_read_b128 v[106:109], v82 offset:4096
	ds_read_b128 v[98:101], v82 offset:4608
	s_waitcnt lgkmcnt(12)
	v_mfma_f32_32x32x16_bf16 v[2:17], v[118:121], v[174:177], v[2:17]
	v_exp_f32_e32 v50, v50
	v_exp_f32_e32 v51, v51
	v_exp_f32_e32 v52, v52
	v_exp_f32_e32 v53, v53
	ds_read_b128 v[178:181], v82 offset:6144
	ds_read_b128 v[174:177], v82 offset:6656
	s_waitcnt lgkmcnt(12)
	v_mfma_f32_32x32x16_bf16 v[18:33], v[118:121], v[170:173], v[18:33]
	v_exp_f32_e32 v54, v54
	v_exp_f32_e32 v55, v55
	v_exp_f32_e32 v56, v56
	v_exp_f32_e32 v57, v57
	s_waitcnt lgkmcnt(10)
	v_mfma_f32_32x32x16_bf16 v[2:17], v[114:117], v[166:169], v[2:17]
	v_exp_f32_e32 v58, v58
	v_exp_f32_e32 v59, v59
	v_exp_f32_e32 v60, v60
	v_exp_f32_e32 v61, v61
	s_waitcnt lgkmcnt(8)
	v_mfma_f32_32x32x16_bf16 v[18:33], v[114:117], v[162:165], v[18:33]
	v_exp_f32_e32 v62, v62
	v_exp_f32_e32 v63, v63
	v_exp_f32_e32 v64, v64
	v_exp_f32_e32 v65, v65
	s_waitcnt vmcnt(0) lgkmcnt(0)
	s_barrier
	s_andn2_b64 vcc, exec, s[62:63]
	s_cbranch_vccnz .LBB0_416
	s_waitcnt lgkmcnt(0)
	ds_read_b128 v[82:85], v242 offset:96
	ds_read_b128 v[86:89], v242 offset:64
	ds_read_b128 v[90:93], v242 offset:32
	ds_read_b128 v[94:97], v242
	s_waitcnt lgkmcnt(3)
	v_mul_f32_e32 v16, v16, v84
	v_mul_f32_e32 v17, v17, v85
	s_waitcnt lgkmcnt(2)
	v_mul_f32_e32 v12, v12, v88
	v_mul_f32_e32 v13, v13, v89
	s_waitcnt lgkmcnt(1)
	v_mul_f32_e32 v8, v8, v92
	v_mul_f32_e32 v9, v9, v93
	s_waitcnt lgkmcnt(0)
	v_mul_f32_e32 v4, v4, v96
	v_mul_f32_e32 v5, v5, v97
	v_mul_f32_e32 v14, v14, v82
	v_mul_f32_e32 v15, v15, v83
	v_mul_f32_e32 v10, v10, v86
	v_mul_f32_e32 v11, v11, v87
	v_mul_f32_e32 v6, v6, v90
	v_mul_f32_e32 v7, v7, v91
	v_mul_f32_e32 v2, v2, v94
	v_mul_f32_e32 v3, v3, v95
	v_mul_f32_e32 v32, v32, v84
	v_mul_f32_e32 v33, v33, v85
	v_mul_f32_e32 v28, v28, v88
	v_mul_f32_e32 v29, v29, v89
	v_mul_f32_e32 v24, v24, v92
	v_mul_f32_e32 v25, v25, v93
	v_mul_f32_e32 v20, v20, v96
	v_mul_f32_e32 v21, v21, v97
	v_mul_f32_e32 v30, v30, v82
	v_mul_f32_e32 v31, v31, v83
	v_mul_f32_e32 v26, v26, v86
	v_mul_f32_e32 v27, v27, v87
	v_mul_f32_e32 v22, v22, v90
	v_mul_f32_e32 v23, v23, v91
	v_mul_f32_e32 v18, v18, v94
	v_mul_f32_e32 v19, v19, v95

; __device__ __forceinline__ void na_apply(f32x16&p0,f32x16&p1,const u32x4_t*mf,bool ok){
;   if(!ok){ const float NEG=-INFINITY;
;     #pragma unroll
;     for(int rr=0;rr<16;++rr){p0[rr]=NEG;p1[rr]=NEG;}
;     return; }
;   #pragma unroll
;   for(int rr=0;rr<16;++rr){ const unsigned w0=mf[rr>>3][(rr>>1)&3], w1=mf[2+(rr>>3)][(rr>>1)&3];
;     p0[rr]+=__builtin_bit_cast(float,(rr&1)?(w0&0xffff0000u):(w0<<16)); p1[rr]+=__builtin_bit_cast(float,(rr&1)?(w1&0xffff0000u):(w1<<16)); }
; }
.LBB0_418:
	s_andn2_b64 vcc, exec, s[62:63]
	s_cbranch_vccnz .LBB0_420
	s_waitcnt vmcnt(3)
	v_lshlrev_b32_e32 v64, 16, v148
	v_and_b32_e32 v65, 0xffff0000, v148
	s_waitcnt vmcnt(2)
	v_lshlrev_b32_e32 v52, 16, v154
	v_and_b32_e32 v53, 0xffff0000, v154
	v_lshlrev_b32_e32 v54, 16, v155
	v_and_b32_e32 v55, 0xffff0000, v155
	v_lshlrev_b32_e32 v56, 16, v156
	v_and_b32_e32 v57, 0xffff0000, v156
	v_lshlrev_b32_e32 v58, 16, v157
	v_and_b32_e32 v59, 0xffff0000, v157
	v_lshlrev_b32_e32 v60, 16, v146
	v_and_b32_e32 v61, 0xffff0000, v146
	v_lshlrev_b32_e32 v62, 16, v147
	v_and_b32_e32 v63, 0xffff0000, v147
	v_add_f32_e32 v46, v46, v64
	v_add_f32_e32 v47, v47, v65
	v_lshlrev_b32_e32 v64, 16, v149
	s_waitcnt vmcnt(0)
	v_lshlrev_b32_e32 v50, 16, v158
	v_and_b32_e32 v51, 0xffff0000, v158
	v_add_f32_e32 v34, v34, v52
	v_add_f32_e32 v35, v35, v53
	v_lshlrev_b32_e32 v52, 16, v159
	v_and_b32_e32 v53, 0xffff0000, v159
	v_add_f32_e32 v36, v36, v54
	v_add_f32_e32 v37, v37, v55
	v_lshlrev_b32_e32 v54, 16, v160
	v_and_b32_e32 v55, 0xffff0000, v160
	v_add_f32_e32 v38, v38, v56
	v_add_f32_e32 v39, v39, v57
	v_lshlrev_b32_e32 v56, 16, v161
	v_and_b32_e32 v57, 0xffff0000, v161
	v_add_f32_e32 v40, v40, v58
	v_add_f32_e32 v41, v41, v59
	v_lshlrev_b32_e32 v58, 16, v150
	v_and_b32_e32 v59, 0xffff0000, v150
	v_add_f32_e32 v42, v42, v60
	v_add_f32_e32 v43, v43, v61
	v_lshlrev_b32_e32 v60, 16, v151
	v_and_b32_e32 v61, 0xffff0000, v151
	v_add_f32_e32 v44, v44, v62
	v_add_f32_e32 v45, v45, v63
	v_lshlrev_b32_e32 v62, 16, v152
	v_and_b32_e32 v63, 0xffff0000, v152
	v_add_f32_e32 v48, v48, v64
	v_lshlrev_b32_e32 v64, 16, v153
	v_and_b32_e32 v65, 0xffff0000, v153
	v_and_b32_e32 v67, 0xffff0000, v149
	v_add_f32_e32 v50, v82, v50
	v_add_f32_e32 v51, v83, v51
	v_add_f32_e32 v52, v84, v52
	v_add_f32_e32 v53, v85, v53
	v_add_f32_e32 v54, v86, v54
	v_add_f32_e32 v55, v87, v55
	v_add_f32_e32 v56, v88, v56
	v_add_f32_e32 v57, v89, v57
	v_add_f32_e32 v58, v90, v58
	v_add_f32_e32 v59, v91, v59
	v_add_f32_e32 v60, v92, v60
	v_add_f32_e32 v61, v93, v61
	v_add_f32_e32 v62, v94, v62
	v_add_f32_e32 v63, v95, v63
	v_add_f32_e32 v64, v96, v64
	v_add_f32_e32 v65, v97, v65
	v_add_f32_e32 v49, v49, v67
	s_branch .LBB0_421

.LBB0_424:
	s_waitcnt lgkmcnt(14)
	v_mfma_f32_32x32x16_bf16 v[2:17], v[126:129], v[170:173], v[2:17]
	v_exp_f32_e32 v50, v50
	v_exp_f32_e32 v51, v51
	v_exp_f32_e32 v52, v52
	v_exp_f32_e32 v53, v53
	s_waitcnt lgkmcnt(12)
	v_mfma_f32_32x32x16_bf16 v[18:33], v[126:129], v[166:169], v[18:33]
	v_exp_f32_e32 v54, v54
	v_exp_f32_e32 v55, v55
	v_exp_f32_e32 v56, v56
	v_exp_f32_e32 v57, v57
	s_waitcnt lgkmcnt(10)
	v_mfma_f32_32x32x16_bf16 v[2:17], v[122:125], v[162:165], v[2:17]
	v_exp_f32_e32 v58, v58
	v_exp_f32_e32 v59, v59
	v_exp_f32_e32 v60, v60
	v_exp_f32_e32 v61, v61
	s_waitcnt lgkmcnt(8)
	v_mfma_f32_32x32x16_bf16 v[18:33], v[122:125], v[142:145], v[18:33]
	v_exp_f32_e32 v62, v62
	v_exp_f32_e32 v63, v63
	v_exp_f32_e32 v64, v64
	v_exp_f32_e32 v65, v65
	s_waitcnt lgkmcnt(6)
	v_mfma_f32_32x32x16_bf16 v[2:17], v[118:121], v[110:113], v[2:17]
	v_exp_f32_e32 v34, v34
	v_exp_f32_e32 v35, v35
	v_exp_f32_e32 v36, v36
	v_exp_f32_e32 v37, v37
	s_waitcnt lgkmcnt(4)
	v_mfma_f32_32x32x16_bf16 v[18:33], v[118:121], v[106:109], v[18:33]
	v_exp_f32_e32 v38, v38
	v_exp_f32_e32 v39, v39
	v_exp_f32_e32 v40, v40
	v_exp_f32_e32 v41, v41
	s_waitcnt lgkmcnt(2)
	v_mfma_f32_32x32x16_bf16 v[2:17], v[114:117], v[102:105], v[2:17]
	v_exp_f32_e32 v42, v42
	v_exp_f32_e32 v43, v43
	v_exp_f32_e32 v44, v44
	v_exp_f32_e32 v45, v45
	s_waitcnt lgkmcnt(0)
	v_mfma_f32_32x32x16_bf16 v[18:33], v[114:117], v[98:101], v[18:33]
	v_exp_f32_e32 v46, v46
	v_exp_f32_e32 v47, v47
	v_exp_f32_e32 v48, v48
	v_exp_f32_e32 v49, v49
	s_andn2_b64 vcc, exec, s[60:61]
	s_cbranch_vccnz .LBB0_426
	s_waitcnt lgkmcnt(0)
	ds_read_b128 v[66:69], v242 offset:96
	ds_read_b128 v[70:73], v242 offset:64
	ds_read_b128 v[74:77], v242 offset:32
	ds_read_b128 v[78:81], v242
	s_waitcnt lgkmcnt(3)
	v_mul_f32_e32 v16, v16, v68
	v_mul_f32_e32 v17, v17, v69
	s_waitcnt lgkmcnt(2)
	v_mul_f32_e32 v12, v12, v72
	v_mul_f32_e32 v13, v13, v73
	s_waitcnt lgkmcnt(1)
	v_mul_f32_e32 v8, v8, v76
	v_mul_f32_e32 v9, v9, v77
	s_waitcnt lgkmcnt(0)
	v_mul_f32_e32 v4, v4, v80
	v_mul_f32_e32 v5, v5, v81
	v_mul_f32_e32 v14, v14, v66
	v_mul_f32_e32 v15, v15, v67
	v_mul_f32_e32 v10, v10, v70
	v_mul_f32_e32 v11, v11, v71
	v_mul_f32_e32 v6, v6, v74
	v_mul_f32_e32 v7, v7, v75
	v_mul_f32_e32 v2, v2, v78
	v_mul_f32_e32 v3, v3, v79
	v_mul_f32_e32 v32, v32, v68
	v_mul_f32_e32 v33, v33, v69
	v_mul_f32_e32 v28, v28, v72
	v_mul_f32_e32 v29, v29, v73
	v_mul_f32_e32 v24, v24, v76
	v_mul_f32_e32 v25, v25, v77
	v_mul_f32_e32 v20, v20, v80
	v_mul_f32_e32 v21, v21, v81
	v_mul_f32_e32 v30, v30, v66
	v_mul_f32_e32 v31, v31, v67
	v_mul_f32_e32 v26, v26, v70
	v_mul_f32_e32 v27, v27, v71
	v_mul_f32_e32 v22, v22, v74
	v_mul_f32_e32 v23, v23, v75
	v_mul_f32_e32 v18, v18, v78
	v_mul_f32_e32 v19, v19, v79

; __device__ __forceinline__ unsigned cvt_pk_bf16(float lo, float hi) { unsigned r; asm volatile("v_cvt_pk_bf16_f32 %0, %1, %2" : "=v"(r) : "v"(lo), "v"(hi)); return r; }
;     __device__ __forceinline__ void operator()(const f32x4 (&acc)[2][2][4][2], const Unit& u, int wr, int wc, int fr, int fq) const {
;     ...
;             for (int m = 0; m < 4; ++m) { const int r = rl + ai * HALF + m * 16; bf16_t* rowp = O + (size_t)(u.pm * BM + r) * ldc + col0;
;                 f32x4 t0 = (f32x4){1.f, 0.f, 1.f, 0.f}, t1 = t0;
;                 if (dorope) { const int pos = tt * 256 - 256 + r; const int pp = (i0 < 16) ? (pos >> 6) : (pos & 63); const f32x4* tb = (const f32x4*)(rope + (pp * 16 + (i0 & 15)) * 2); t0 = tb[0]; t1 = tb[1]; }
; #pragma unroll
;                 for (int bj = 0; bj < 2; ++bj) { const f32x4 v0 = acc[ai][bj][m][0], v1 = acc[ai][bj][m][1]; u32x4 w;
;                     w.x = cvt_pk_bf16((v0[0] * t0[0] - v0[1] * t0[1]) * sc, (v0[0] * t0[1] + v0[1] * t0[0]) * sc);
;                     w.y = cvt_pk_bf16((v0[2] * t0[2] - v0[3] * t0[3]) * sc, (v0[2] * t0[3] + v0[3] * t0[2]) * sc);
;                     w.z = cvt_pk_bf16((v1[0] * t1[0] - v1[1] * t1[1]) * sc, (v1[0] * t1[1] + v1[1] * t1[0]) * sc);
;                     w.w = cvt_pk_bf16((v1[2] * t1[2] - v1[3] * t1[3]) * sc, (v1[2] * t1[3] + v1[3] * t1[2]) * sc);
;                     *(u32x4*)(rowp + bj * HALF) = w; } }
.Lrope_skip_1:
.LBB0_1035:
	s_cmp_lt_i32 s62, 4
	s_cselect_b64 vcc, -1, 0
	s_lshl_b32 s55, s64, 8
	v_add_u32_e32 v189, s55, v157
	v_mov_b64_e32 v[190:191], s[44:45]
	s_waitcnt vmcnt(2)
	v_mul_f32_e32 v192, v124, v198
	v_mul_f32_e32 v193, v125, v199
	v_mad_i64_i32 v[190:191], s[66:67], v189, s79, v[190:191]
	v_sub_f32_e32 v189, v192, v193
	v_mul_f32_e32 v124, v124, v199
	v_mul_f32_e32 v125, v125, v198
	v_mul_f32_e32 v192, v126, v200
	v_mul_f32_e32 v193, v127, v201
	v_mul_f32_e32 v126, v126, v201
	v_mul_f32_e32 v127, v127, v200
	v_cndmask_b32_e32 v188, 1.0, v187, vcc
	s_and_b64 vcc, exec, s[10:11]
	s_cbranch_vccnz .Lrope_skip_2
	v_add_u32_e32 v210, s33, v164
	v_ashrrev_i32_e32 v210, 6, v210
	v_cndmask_b32_e64 v210, v161, v210, s[6:7]
	v_lshl_or_b32 v210, v210, 5, v158
	v_ashrrev_i32_e32 v211, 31, v210
	v_lshl_add_u64 v[214:215], v[210:211], 2, s[50:51]
	global_load_dwordx4 v[210:213], v[214:215], off offset:16
	s_nop 0
	global_load_dwordx4 v[214:217], v[214:215], off
.Lrope_skip_2:
	v_add_f32_e32 v124, v124, v125
	v_sub_f32_e32 v125, v192, v193
	v_add_f32_e32 v126, v126, v127
	v_mul_f32_e32 v124, v188, v124
	v_mul_f32_e32 v125, v188, v125
	v_mul_f32_e32 v126, v188, v126
	v_mul_f32_e32 v189, v188, v189
	v_cvt_pk_bf16_f32 v124, v189, v124
	v_cvt_pk_bf16_f32 v125, v125, v126
	v_mul_f32_e32 v126, v120, v194
	v_mul_f32_e32 v127, v121, v195
	v_mul_f32_e32 v120, v120, v195
	v_mul_f32_e32 v121, v121, v194
	v_sub_f32_e32 v126, v126, v127
	v_add_f32_e32 v120, v120, v121
	v_mul_f32_e32 v126, v188, v126
	v_mul_f32_e32 v120, v188, v120
	v_cvt_pk_bf16_f32 v126, v126, v120
	v_mul_f32_e32 v120, v122, v196
	v_mul_f32_e32 v121, v123, v197
	v_lshl_or_b32 v154, s62, 8, v170
	v_sub_f32_e32 v120, v120, v121
	v_mul_f32_e32 v127, v188, v120
	v_mul_f32_e32 v120, v122, v197
	v_mul_f32_e32 v121, v123, v196
	v_ashrrev_i32_e32 v155, 31, v154
	v_add_f32_e32 v120, v120, v121
	v_mul_f32_e32 v120, v188, v120
	v_cvt_pk_bf16_f32 v127, v127, v120
	v_mul_f32_e32 v120, v116, v198
	v_mul_f32_e32 v121, v117, v199
	v_mul_f32_e32 v116, v116, v199
	v_mul_f32_e32 v117, v117, v198
	v_sub_f32_e32 v120, v120, v121
	v_add_f32_e32 v116, v116, v117
	v_lshl_add_u64 v[190:191], v[154:155], 1, v[190:191]
	v_mul_f32_e32 v120, v188, v120
	v_mul_f32_e32 v116, v188, v116
	global_store_dwordx4 v[190:191], v[124:127], off
	v_cvt_pk_bf16_f32 v116, v120, v116
	v_mul_f32_e32 v120, v118, v200
	v_mul_f32_e32 v121, v119, v201
	v_mul_f32_e32 v118, v118, v201
	v_mul_f32_e32 v119, v119, v200
	v_sub_f32_e32 v117, v120, v121
	v_add_f32_e32 v118, v118, v119
	v_mul_f32_e32 v117, v188, v117
	v_mul_f32_e32 v118, v188, v118
	v_cvt_pk_bf16_f32 v117, v117, v118
	v_mul_f32_e32 v118, v112, v194
	v_mul_f32_e32 v119, v113, v195
	v_mul_f32_e32 v112, v112, v195
	v_mul_f32_e32 v113, v113, v194
	v_sub_f32_e32 v118, v118, v119
	v_add_f32_e32 v112, v112, v113
	v_mul_f32_e32 v118, v188, v118
	v_mul_f32_e32 v112, v188, v112
	v_cvt_pk_bf16_f32 v118, v118, v112
	v_mul_f32_e32 v112, v114, v196
	v_mul_f32_e32 v113, v115, v197
	s_and_b64 vcc, exec, s[10:11]
	v_sub_f32_e32 v112, v112, v113
	v_mul_f32_e32 v119, v188, v112
	v_mul_f32_e32 v112, v114, v197
	v_mul_f32_e32 v113, v115, v196
	v_mov_b32_e32 v130, 1.0
	v_add_f32_e32 v112, v112, v113
	v_mul_f32_e32 v112, v188, v112
	v_cvt_pk_bf16_f32 v119, v119, v112
	v_mov_b32_e32 v131, 0
	v_mov_b32_e32 v112, 1.0
	v_mov_b32_e32 v113, 0
	v_mov_b32_e32 v114, 1.0
	v_mov_b32_e32 v115, 0
	global_store_dwordx4 v[190:191], v[116:119], off offset:256
	s_nop 1

; __device__ __forceinline__ unsigned cvt_pk_bf16(float lo, float hi) { unsigned r; asm volatile("v_cvt_pk_bf16_f32 %0, %1, %2" : "=v"(r) : "v"(lo), "v"(hi)); return r; }
;     __device__ __forceinline__ void operator()(const f32x4 (&acc)[2][2][4][2], const Unit& u, int wr, int wc, int fr, int fq) const {
;     ...
;             for (int m = 0; m < 4; ++m) { const int r = rl + ai * HALF + m * 16; bf16_t* rowp = O + (size_t)(u.pm * BM + r) * ldc + col0;
;                 f32x4 t0 = (f32x4){1.f, 0.f, 1.f, 0.f}, t1 = t0;
;                 if (dorope) { const int pos = tt * 256 - 256 + r; const int pp = (i0 < 16) ? (pos >> 6) : (pos & 63); const f32x4* tb = (const f32x4*)(rope + (pp * 16 + (i0 & 15)) * 2); t0 = tb[0]; t1 = tb[1]; }
; #pragma unroll
;                 for (int bj = 0; bj < 2; ++bj) { const f32x4 v0 = acc[ai][bj][m][0], v1 = acc[ai][bj][m][1]; u32x4 w;
;                     w.x = cvt_pk_bf16((v0[0] * t0[0] - v0[1] * t0[1]) * sc, (v0[0] * t0[1] + v0[1] * t0[0]) * sc);
;                     w.y = cvt_pk_bf16((v0[2] * t0[2] - v0[3] * t0[3]) * sc, (v0[2] * t0[3] + v0[3] * t0[2]) * sc);
;                     w.z = cvt_pk_bf16((v1[0] * t1[0] - v1[1] * t1[1]) * sc, (v1[0] * t1[1] + v1[1] * t1[0]) * sc);
;                     w.w = cvt_pk_bf16((v1[2] * t1[2] - v1[3] * t1[3]) * sc, (v1[2] * t1[3] + v1[3] * t1[2]) * sc);
;                     *(u32x4*)(rowp + bj * HALF) = w; } }
.Lrope_skip_3:
	v_mul_f32_e32 v118, v108, v206
	v_mul_f32_e32 v119, v109, v207
	v_mul_f32_e32 v108, v108, v207
	v_mul_f32_e32 v109, v109, v206
	v_sub_f32_e32 v118, v118, v119
	v_add_f32_e32 v108, v108, v109
	v_mul_f32_e32 v118, v188, v118
	v_mul_f32_e32 v108, v188, v108
	v_cvt_pk_bf16_f32 v108, v118, v108
	v_mul_f32_e32 v118, v110, v208
	v_mul_f32_e32 v119, v111, v209
	v_mul_f32_e32 v110, v110, v209
	v_mul_f32_e32 v111, v111, v208
	v_sub_f32_e32 v109, v118, v119
	v_add_f32_e32 v110, v110, v111
	v_mul_f32_e32 v109, v188, v109
	v_mul_f32_e32 v110, v188, v110
	v_cvt_pk_bf16_f32 v109, v109, v110
	v_mul_f32_e32 v110, v104, v202
	v_mul_f32_e32 v111, v105, v203
	v_mul_f32_e32 v104, v104, v203
	v_mul_f32_e32 v105, v105, v202
	v_sub_f32_e32 v110, v110, v111
	v_add_f32_e32 v104, v104, v105
	v_mul_f32_e32 v110, v188, v110
	v_mul_f32_e32 v104, v188, v104
	v_cvt_pk_bf16_f32 v110, v110, v104
	v_mul_f32_e32 v104, v106, v204
	v_mul_f32_e32 v105, v107, v205
	v_lshl_add_u64 v[116:117], v[154:155], 1, v[116:117]
	v_sub_f32_e32 v104, v104, v105
	v_mul_f32_e32 v111, v188, v104
	v_mul_f32_e32 v104, v106, v205
	v_mul_f32_e32 v105, v107, v204
	s_and_b64 vcc, exec, s[10:11]
	v_add_f32_e32 v104, v104, v105
	v_mul_f32_e32 v104, v188, v104
	v_cvt_pk_bf16_f32 v111, v111, v104
	v_mul_f32_e32 v104, v100, v206
	v_mul_f32_e32 v105, v101, v207
	v_mul_f32_e32 v100, v100, v207
	v_mul_f32_e32 v101, v101, v206
	v_sub_f32_e32 v104, v104, v105
	v_add_f32_e32 v100, v100, v101
	v_mul_f32_e32 v104, v188, v104
	v_mul_f32_e32 v100, v188, v100
	global_store_dwordx4 v[116:117], v[108:111], off
	v_cvt_pk_bf16_f32 v100, v104, v100
	v_mul_f32_e32 v104, v102, v208
	v_mul_f32_e32 v105, v103, v209
	v_mul_f32_e32 v102, v102, v209
	v_mul_f32_e32 v103, v103, v208
	v_sub_f32_e32 v101, v104, v105
	v_add_f32_e32 v102, v102, v103
	v_mul_f32_e32 v101, v188, v101
	v_mul_f32_e32 v102, v188, v102
	v_cvt_pk_bf16_f32 v101, v101, v102
	v_mul_f32_e32 v102, v96, v202
	v_mul_f32_e32 v103, v97, v203
	v_mul_f32_e32 v96, v96, v203
	v_mul_f32_e32 v97, v97, v202
	v_sub_f32_e32 v102, v102, v103
	v_add_f32_e32 v96, v96, v97
	v_mul_f32_e32 v102, v188, v102
	v_mul_f32_e32 v96, v188, v96
	v_cvt_pk_bf16_f32 v102, v102, v96
	v_mul_f32_e32 v96, v98, v204
	v_mul_f32_e32 v97, v99, v205
	v_mov_b32_e32 v104, 1.0
	v_sub_f32_e32 v96, v96, v97
	v_mul_f32_e32 v103, v188, v96
	v_mul_f32_e32 v96, v98, v205
	v_mul_f32_e32 v97, v99, v204
	v_mov_b32_e32 v98, 1.0
	v_add_f32_e32 v96, v96, v97
	v_mul_f32_e32 v96, v188, v96
	v_cvt_pk_bf16_f32 v103, v103, v96
	global_store_dwordx4 v[116:117], v[100:103], off offset:256
	v_mov_b32_e32 v97, 0
	v_mov_b32_e32 v96, 1.0
	v_mov_b32_e32 v99, 0
	v_mov_b32_e32 v100, 1.0
	v_mov_b32_e32 v101, 0
	v_mov_b32_e32 v102, 1.0
	v_mov_b32_e32 v103, 0
	v_mov_b32_e32 v105, 0
	s_nop 1

; __device__ __forceinline__ unsigned cvt_pk_bf16(float lo, float hi) { unsigned r; asm volatile("v_cvt_pk_bf16_f32 %0, %1, %2" : "=v"(r) : "v"(lo), "v"(hi)); return r; }
;     __device__ __forceinline__ void operator()(const f32x4 (&acc)[2][2][4][2], const Unit& u, int wr, int wc, int fr, int fq) const {
;     ...
;             for (int m = 0; m < 4; ++m) { const int r = rl + ai * HALF + m * 16; bf16_t* rowp = O + (size_t)(u.pm * BM + r) * ldc + col0;
;                 f32x4 t0 = (f32x4){1.f, 0.f, 1.f, 0.f}, t1 = t0;
;                 if (dorope) { const int pos = tt * 256 - 256 + r; const int pp = (i0 < 16) ? (pos >> 6) : (pos & 63); const f32x4* tb = (const f32x4*)(rope + (pp * 16 + (i0 & 15)) * 2); t0 = tb[0]; t1 = tb[1]; }
; #pragma unroll
;                 for (int bj = 0; bj < 2; ++bj) { const f32x4 v0 = acc[ai][bj][m][0], v1 = acc[ai][bj][m][1]; u32x4 w;
;                     w.x = cvt_pk_bf16((v0[0] * t0[0] - v0[1] * t0[1]) * sc, (v0[0] * t0[1] + v0[1] * t0[0]) * sc);
;                     w.y = cvt_pk_bf16((v0[2] * t0[2] - v0[3] * t0[3]) * sc, (v0[2] * t0[3] + v0[3] * t0[2]) * sc);
;                     w.z = cvt_pk_bf16((v1[0] * t1[0] - v1[1] * t1[1]) * sc, (v1[0] * t1[1] + v1[1] * t1[0]) * sc);
;                     w.w = cvt_pk_bf16((v1[2] * t1[2] - v1[3] * t1[3]) * sc, (v1[2] * t1[3] + v1[3] * t1[2]) * sc);
;                     *(u32x4*)(rowp + bj * HALF) = w; } }
.Lrope_skip_4:
	v_mul_f32_e32 v108, v92, v214
	v_mul_f32_e32 v109, v93, v215
	v_mul_f32_e32 v92, v92, v215
	v_mul_f32_e32 v93, v93, v214
	v_sub_f32_e32 v108, v108, v109
	v_add_f32_e32 v92, v92, v93
	v_mul_f32_e32 v108, v188, v108
	v_mul_f32_e32 v92, v188, v92
	v_cvt_pk_bf16_f32 v92, v108, v92
	v_mul_f32_e32 v108, v94, v216
	v_mul_f32_e32 v109, v95, v217
	v_mul_f32_e32 v94, v94, v217
	v_mul_f32_e32 v95, v95, v216
	v_sub_f32_e32 v93, v108, v109
	v_add_f32_e32 v94, v94, v95
	v_mul_f32_e32 v93, v188, v93
	v_mul_f32_e32 v94, v188, v94
	v_cvt_pk_bf16_f32 v93, v93, v94
	v_mul_f32_e32 v94, v88, v210
	v_mul_f32_e32 v95, v89, v211
	v_mul_f32_e32 v88, v88, v211
	v_mul_f32_e32 v89, v89, v210
	v_sub_f32_e32 v94, v94, v95
	v_add_f32_e32 v88, v88, v89
	v_mul_f32_e32 v94, v188, v94
	v_mul_f32_e32 v88, v188, v88
	v_cvt_pk_bf16_f32 v94, v94, v88
	v_mul_f32_e32 v88, v90, v212
	v_mul_f32_e32 v89, v91, v213
	v_lshl_add_u64 v[106:107], v[154:155], 1, v[106:107]
	v_sub_f32_e32 v88, v88, v89
	v_mul_f32_e32 v95, v188, v88
	v_mul_f32_e32 v88, v90, v213
	v_mul_f32_e32 v89, v91, v212
	s_and_b64 vcc, exec, s[10:11]
	v_add_f32_e32 v88, v88, v89
	v_mul_f32_e32 v88, v188, v88
	v_cvt_pk_bf16_f32 v95, v95, v88
	v_mul_f32_e32 v88, v84, v214
	v_mul_f32_e32 v89, v85, v215
	v_mul_f32_e32 v84, v84, v215
	v_mul_f32_e32 v85, v85, v214
	v_sub_f32_e32 v88, v88, v89
	v_add_f32_e32 v84, v84, v85
	v_mul_f32_e32 v88, v188, v88
	v_mul_f32_e32 v84, v188, v84
	global_store_dwordx4 v[106:107], v[92:95], off
	v_cvt_pk_bf16_f32 v84, v88, v84
	v_mul_f32_e32 v88, v86, v216
	v_mul_f32_e32 v89, v87, v217
	v_mul_f32_e32 v86, v86, v217
	v_mul_f32_e32 v87, v87, v216
	v_sub_f32_e32 v85, v88, v89
	v_add_f32_e32 v86, v86, v87
	v_mul_f32_e32 v85, v188, v85
	v_mul_f32_e32 v86, v188, v86
	v_cvt_pk_bf16_f32 v85, v85, v86
	v_mul_f32_e32 v86, v80, v210
	v_mul_f32_e32 v87, v81, v211
	v_mul_f32_e32 v80, v80, v211
	v_mul_f32_e32 v81, v81, v210
	v_sub_f32_e32 v86, v86, v87
	v_add_f32_e32 v80, v80, v81
	v_mul_f32_e32 v86, v188, v86
	v_mul_f32_e32 v80, v188, v80
	v_cvt_pk_bf16_f32 v86, v86, v80
	v_mul_f32_e32 v80, v82, v212
	v_mul_f32_e32 v81, v83, v213
	v_mov_b32_e32 v98, 1.0
	v_sub_f32_e32 v80, v80, v81
	v_mul_f32_e32 v87, v188, v80
	v_mul_f32_e32 v80, v82, v213
	v_mul_f32_e32 v81, v83, v212
	v_mov_b32_e32 v99, 0
	v_add_f32_e32 v80, v80, v81
	v_mul_f32_e32 v80, v188, v80
	v_cvt_pk_bf16_f32 v87, v87, v80
	v_mov_b32_e32 v80, 1.0
	v_mov_b32_e32 v81, 0
	v_mov_b32_e32 v82, 1.0
	v_mov_b32_e32 v83, 0
	global_store_dwordx4 v[106:107], v[84:87], off offset:256
	s_nop 1

; __device__ __forceinline__ unsigned cvt_pk_bf16(float lo, float hi) { unsigned r; asm volatile("v_cvt_pk_bf16_f32 %0, %1, %2" : "=v"(r) : "v"(lo), "v"(hi)); return r; }
;     __device__ __forceinline__ void operator()(const f32x4 (&acc)[2][2][4][2], const Unit& u, int wr, int wc, int fr, int fq) const {
;     ...
;             for (int m = 0; m < 4; ++m) { const int r = rl + ai * HALF + m * 16; bf16_t* rowp = O + (size_t)(u.pm * BM + r) * ldc + col0;
;                 f32x4 t0 = (f32x4){1.f, 0.f, 1.f, 0.f}, t1 = t0;
;                 if (dorope) { const int pos = tt * 256 - 256 + r; const int pp = (i0 < 16) ? (pos >> 6) : (pos & 63); const f32x4* tb = (const f32x4*)(rope + (pp * 16 + (i0 & 15)) * 2); t0 = tb[0]; t1 = tb[1]; }
; #pragma unroll
;                 for (int bj = 0; bj < 2; ++bj) { const f32x4 v0 = acc[ai][bj][m][0], v1 = acc[ai][bj][m][1]; u32x4 w;
;                     w.x = cvt_pk_bf16((v0[0] * t0[0] - v0[1] * t0[1]) * sc, (v0[0] * t0[1] + v0[1] * t0[0]) * sc);
;                     w.y = cvt_pk_bf16((v0[2] * t0[2] - v0[3] * t0[3]) * sc, (v0[2] * t0[3] + v0[3] * t0[2]) * sc);
;                     w.z = cvt_pk_bf16((v1[0] * t1[0] - v1[1] * t1[1]) * sc, (v1[0] * t1[1] + v1[1] * t1[0]) * sc);
;                     w.w = cvt_pk_bf16((v1[2] * t1[2] - v1[3] * t1[3]) * sc, (v1[2] * t1[3] + v1[3] * t1[2]) * sc);
;                     *(u32x4*)(rowp + bj * HALF) = w; } }
.Lrope_skip_5:
	v_mul_f32_e32 v86, v76, v198
	v_mul_f32_e32 v87, v77, v199
	v_mul_f32_e32 v76, v76, v199
	v_mul_f32_e32 v77, v77, v198
	v_sub_f32_e32 v86, v86, v87
	v_add_f32_e32 v76, v76, v77
	v_mul_f32_e32 v86, v188, v86
	v_mul_f32_e32 v76, v188, v76
	v_cvt_pk_bf16_f32 v76, v86, v76
	v_mul_f32_e32 v86, v78, v200
	v_mul_f32_e32 v87, v79, v201
	v_mul_f32_e32 v78, v78, v201
	v_mul_f32_e32 v79, v79, v200
	v_sub_f32_e32 v77, v86, v87
	v_add_f32_e32 v78, v78, v79
	v_mul_f32_e32 v77, v188, v77
	v_mul_f32_e32 v78, v188, v78
	v_cvt_pk_bf16_f32 v77, v77, v78
	v_mul_f32_e32 v78, v72, v194
	v_mul_f32_e32 v79, v73, v195
	v_mul_f32_e32 v72, v72, v195
	v_mul_f32_e32 v73, v73, v194
	v_sub_f32_e32 v78, v78, v79
	v_add_f32_e32 v72, v72, v73
	v_mul_f32_e32 v78, v188, v78
	v_mul_f32_e32 v72, v188, v72
	v_cvt_pk_bf16_f32 v78, v78, v72
	v_mul_f32_e32 v72, v74, v196
	v_mul_f32_e32 v73, v75, v197
	v_lshl_add_u64 v[84:85], v[154:155], 1, v[84:85]
	v_sub_f32_e32 v72, v72, v73
	v_mul_f32_e32 v79, v188, v72
	v_mul_f32_e32 v72, v74, v197
	v_mul_f32_e32 v73, v75, v196
	s_and_b64 vcc, exec, s[10:11]
	v_add_f32_e32 v72, v72, v73
	v_mul_f32_e32 v72, v188, v72
	v_cvt_pk_bf16_f32 v79, v79, v72
	v_mul_f32_e32 v72, v68, v198
	v_mul_f32_e32 v73, v69, v199
	v_mul_f32_e32 v68, v68, v199
	v_mul_f32_e32 v69, v69, v198
	v_sub_f32_e32 v72, v72, v73
	v_add_f32_e32 v68, v68, v69
	v_mul_f32_e32 v72, v188, v72
	v_mul_f32_e32 v68, v188, v68
	global_store_dwordx4 v[84:85], v[76:79], off
	v_cvt_pk_bf16_f32 v68, v72, v68
	v_mul_f32_e32 v72, v70, v200
	v_mul_f32_e32 v73, v71, v201
	v_mul_f32_e32 v70, v70, v201
	v_mul_f32_e32 v71, v71, v200
	v_sub_f32_e32 v69, v72, v73
	v_add_f32_e32 v70, v70, v71
	v_mul_f32_e32 v69, v188, v69
	v_mul_f32_e32 v70, v188, v70
	v_cvt_pk_bf16_f32 v69, v69, v70
	v_mul_f32_e32 v70, v64, v194
	v_mul_f32_e32 v71, v65, v195
	v_mul_f32_e32 v64, v64, v195
	v_mul_f32_e32 v65, v65, v194
	v_sub_f32_e32 v70, v70, v71
	v_add_f32_e32 v64, v64, v65
	v_mul_f32_e32 v70, v188, v70
	v_mul_f32_e32 v64, v188, v64
	v_cvt_pk_bf16_f32 v70, v70, v64
	v_mul_f32_e32 v64, v66, v196
	v_mul_f32_e32 v65, v67, v197
	v_mov_b32_e32 v72, 1.0
	v_sub_f32_e32 v64, v64, v65
	v_mul_f32_e32 v71, v188, v64
	v_mul_f32_e32 v64, v66, v197
	v_mul_f32_e32 v65, v67, v196
	v_mov_b32_e32 v66, 1.0
	v_add_f32_e32 v64, v64, v65
	v_mul_f32_e32 v64, v188, v64
	v_cvt_pk_bf16_f32 v71, v71, v64
	global_store_dwordx4 v[84:85], v[68:71], off offset:256
	v_mov_b32_e32 v65, 0
	v_mov_b32_e32 v64, 1.0
	v_mov_b32_e32 v67, 0
	v_mov_b32_e32 v68, 1.0
	v_mov_b32_e32 v69, 0
	v_mov_b32_e32 v70, 1.0
	v_mov_b32_e32 v71, 0
	v_mov_b32_e32 v73, 0
	s_nop 1

; __device__ __forceinline__ unsigned cvt_pk_bf16(float lo, float hi) { unsigned r; asm volatile("v_cvt_pk_bf16_f32 %0, %1, %2" : "=v"(r) : "v"(lo), "v"(hi)); return r; }
;     __device__ __forceinline__ void operator()(const f32x4 (&acc)[2][2][4][2], const Unit& u, int wr, int wc, int fr, int fq) const {
;     ...
;             for (int m = 0; m < 4; ++m) { const int r = rl + ai * HALF + m * 16; bf16_t* rowp = O + (size_t)(u.pm * BM + r) * ldc + col0;
;                 f32x4 t0 = (f32x4){1.f, 0.f, 1.f, 0.f}, t1 = t0;
;                 if (dorope) { const int pos = tt * 256 - 256 + r; const int pp = (i0 < 16) ? (pos >> 6) : (pos & 63); const f32x4* tb = (const f32x4*)(rope + (pp * 16 + (i0 & 15)) * 2); t0 = tb[0]; t1 = tb[1]; }
; #pragma unroll
;                 for (int bj = 0; bj < 2; ++bj) { const f32x4 v0 = acc[ai][bj][m][0], v1 = acc[ai][bj][m][1]; u32x4 w;
;                     w.x = cvt_pk_bf16((v0[0] * t0[0] - v0[1] * t0[1]) * sc, (v0[0] * t0[1] + v0[1] * t0[0]) * sc);
;                     w.y = cvt_pk_bf16((v0[2] * t0[2] - v0[3] * t0[3]) * sc, (v0[2] * t0[3] + v0[3] * t0[2]) * sc);
;                     w.z = cvt_pk_bf16((v1[0] * t1[0] - v1[1] * t1[1]) * sc, (v1[0] * t1[1] + v1[1] * t1[0]) * sc);
;                     w.w = cvt_pk_bf16((v1[2] * t1[2] - v1[3] * t1[3]) * sc, (v1[2] * t1[3] + v1[3] * t1[2]) * sc);
;                     *(u32x4*)(rowp + bj * HALF) = w; } }
.Lrope_skip_6:
	v_mul_f32_e32 v76, v60, v206
	v_mul_f32_e32 v77, v61, v207
	v_mul_f32_e32 v60, v60, v207
	v_mul_f32_e32 v61, v61, v206
	v_sub_f32_e32 v76, v76, v77
	v_add_f32_e32 v60, v60, v61
	v_mul_f32_e32 v76, v188, v76
	v_mul_f32_e32 v60, v188, v60
	v_cvt_pk_bf16_f32 v60, v76, v60
	v_mul_f32_e32 v76, v62, v208
	v_mul_f32_e32 v77, v63, v209
	v_mul_f32_e32 v62, v62, v209
	v_mul_f32_e32 v63, v63, v208
	v_sub_f32_e32 v61, v76, v77
	v_add_f32_e32 v62, v62, v63
	v_mul_f32_e32 v61, v188, v61
	v_mul_f32_e32 v62, v188, v62
	v_cvt_pk_bf16_f32 v61, v61, v62
	v_mul_f32_e32 v62, v56, v202
	v_mul_f32_e32 v63, v57, v203
	v_mul_f32_e32 v56, v56, v203
	v_mul_f32_e32 v57, v57, v202
	v_sub_f32_e32 v62, v62, v63
	v_add_f32_e32 v56, v56, v57
	v_mul_f32_e32 v62, v188, v62
	v_mul_f32_e32 v56, v188, v56
	v_cvt_pk_bf16_f32 v62, v62, v56
	v_mul_f32_e32 v56, v58, v204
	v_mul_f32_e32 v57, v59, v205
	v_lshl_add_u64 v[74:75], v[154:155], 1, v[74:75]
	v_sub_f32_e32 v56, v56, v57
	v_mul_f32_e32 v63, v188, v56
	v_mul_f32_e32 v56, v58, v205
	v_mul_f32_e32 v57, v59, v204
	s_and_b64 vcc, exec, s[10:11]
	v_add_f32_e32 v56, v56, v57
	v_mul_f32_e32 v56, v188, v56
	v_cvt_pk_bf16_f32 v63, v63, v56
	v_mul_f32_e32 v56, v52, v206
	v_mul_f32_e32 v57, v53, v207
	v_mul_f32_e32 v52, v52, v207
	v_mul_f32_e32 v53, v53, v206
	v_sub_f32_e32 v56, v56, v57
	v_add_f32_e32 v52, v52, v53
	v_mul_f32_e32 v56, v188, v56
	v_mul_f32_e32 v52, v188, v52
	global_store_dwordx4 v[74:75], v[60:63], off
	v_cvt_pk_bf16_f32 v52, v56, v52
	v_mul_f32_e32 v56, v54, v208
	v_mul_f32_e32 v57, v55, v209
	v_mul_f32_e32 v54, v54, v209
	v_mul_f32_e32 v55, v55, v208
	v_sub_f32_e32 v53, v56, v57
	v_add_f32_e32 v54, v54, v55
	v_mul_f32_e32 v53, v188, v53
	v_mul_f32_e32 v54, v188, v54
	v_cvt_pk_bf16_f32 v53, v53, v54
	v_mul_f32_e32 v54, v48, v202
	v_mul_f32_e32 v55, v49, v203
	v_mul_f32_e32 v48, v48, v203
	v_mul_f32_e32 v49, v49, v202
	v_sub_f32_e32 v54, v54, v55
	v_add_f32_e32 v48, v48, v49
	v_mul_f32_e32 v54, v188, v54
	v_mul_f32_e32 v48, v188, v48
	v_cvt_pk_bf16_f32 v54, v54, v48
	v_mul_f32_e32 v48, v50, v204
	v_mul_f32_e32 v49, v51, v205
	v_mov_b32_e32 v66, 1.0
	v_sub_f32_e32 v48, v48, v49
	v_mul_f32_e32 v55, v188, v48
	v_mul_f32_e32 v48, v50, v205
	v_mul_f32_e32 v49, v51, v204
	v_mov_b32_e32 v67, 0
	v_add_f32_e32 v48, v48, v49
	v_mul_f32_e32 v48, v188, v48
	v_cvt_pk_bf16_f32 v55, v55, v48
	v_mov_b32_e32 v48, 1.0
	v_mov_b32_e32 v49, 0
	v_mov_b32_e32 v50, 1.0
	v_mov_b32_e32 v51, 0
	global_store_dwordx4 v[74:75], v[52:55], off offset:256
	s_nop 1

; __device__ __forceinline__ unsigned cvt_pk_bf16(float lo, float hi) { unsigned r; asm volatile("v_cvt_pk_bf16_f32 %0, %1, %2" : "=v"(r) : "v"(lo), "v"(hi)); return r; }
;     __device__ __forceinline__ void operator()(const f32x4 (&acc)[2][2][4][2], const Unit& u, int wr, int wc, int fr, int fq) const {
;     ...
;             for (int m = 0; m < 4; ++m) { const int r = rl + ai * HALF + m * 16; bf16_t* rowp = O + (size_t)(u.pm * BM + r) * ldc + col0;
;                 f32x4 t0 = (f32x4){1.f, 0.f, 1.f, 0.f}, t1 = t0;
;                 if (dorope) { const int pos = tt * 256 - 256 + r; const int pp = (i0 < 16) ? (pos >> 6) : (pos & 63); const f32x4* tb = (const f32x4*)(rope + (pp * 16 + (i0 & 15)) * 2); t0 = tb[0]; t1 = tb[1]; }
; #pragma unroll
;                 for (int bj = 0; bj < 2; ++bj) { const f32x4 v0 = acc[ai][bj][m][0], v1 = acc[ai][bj][m][1]; u32x4 w;
;                     w.x = cvt_pk_bf16((v0[0] * t0[0] - v0[1] * t0[1]) * sc, (v0[0] * t0[1] + v0[1] * t0[0]) * sc);
;                     w.y = cvt_pk_bf16((v0[2] * t0[2] - v0[3] * t0[3]) * sc, (v0[2] * t0[3] + v0[3] * t0[2]) * sc);
;                     w.z = cvt_pk_bf16((v1[0] * t1[0] - v1[1] * t1[1]) * sc, (v1[0] * t1[1] + v1[1] * t1[0]) * sc);
;                     w.w = cvt_pk_bf16((v1[2] * t1[2] - v1[3] * t1[3]) * sc, (v1[2] * t1[3] + v1[3] * t1[2]) * sc);
;                     *(u32x4*)(rowp + bj * HALF) = w; } }
.Lrope_skip_7:
	v_mul_f32_e32 v54, v44, v214
	v_mul_f32_e32 v55, v45, v215
	v_mul_f32_e32 v44, v44, v215
	v_mul_f32_e32 v45, v45, v214
	v_sub_f32_e32 v54, v54, v55
	v_add_f32_e32 v44, v44, v45
	v_mul_f32_e32 v54, v188, v54
	v_mul_f32_e32 v44, v188, v44
	v_cvt_pk_bf16_f32 v44, v54, v44
	v_mul_f32_e32 v54, v46, v216
	v_mul_f32_e32 v55, v47, v217
	v_mul_f32_e32 v46, v46, v217
	v_mul_f32_e32 v47, v47, v216
	v_sub_f32_e32 v45, v54, v55
	v_add_f32_e32 v46, v46, v47
	v_mul_f32_e32 v45, v188, v45
	v_mul_f32_e32 v46, v188, v46
	v_cvt_pk_bf16_f32 v45, v45, v46
	v_mul_f32_e32 v46, v40, v210
	v_mul_f32_e32 v47, v41, v211
	v_mul_f32_e32 v40, v40, v211
	v_mul_f32_e32 v41, v41, v210
	v_sub_f32_e32 v46, v46, v47
	v_add_f32_e32 v40, v40, v41
	v_mul_f32_e32 v46, v188, v46
	v_mul_f32_e32 v40, v188, v40
	v_cvt_pk_bf16_f32 v46, v46, v40
	v_mul_f32_e32 v40, v42, v212
	v_mul_f32_e32 v41, v43, v213
	v_lshl_add_u64 v[52:53], v[154:155], 1, v[52:53]
	v_sub_f32_e32 v40, v40, v41
	v_mul_f32_e32 v47, v188, v40
	v_mul_f32_e32 v40, v42, v213
	v_mul_f32_e32 v41, v43, v212
	s_and_b64 vcc, exec, s[10:11]
	v_add_f32_e32 v40, v40, v41
	v_mul_f32_e32 v40, v188, v40
	v_cvt_pk_bf16_f32 v47, v47, v40
	v_mul_f32_e32 v40, v36, v214
	v_mul_f32_e32 v41, v37, v215
	v_mul_f32_e32 v36, v36, v215
	v_mul_f32_e32 v37, v37, v214
	v_sub_f32_e32 v40, v40, v41
	v_add_f32_e32 v36, v36, v37
	v_mul_f32_e32 v40, v188, v40
	v_mul_f32_e32 v36, v188, v36
	global_store_dwordx4 v[52:53], v[44:47], off
	v_cvt_pk_bf16_f32 v36, v40, v36
	v_mul_f32_e32 v40, v38, v216
	v_mul_f32_e32 v41, v39, v217
	v_mul_f32_e32 v38, v38, v217
	v_mul_f32_e32 v39, v39, v216
	v_sub_f32_e32 v37, v40, v41
	v_add_f32_e32 v38, v38, v39
	v_mul_f32_e32 v37, v188, v37
	v_mul_f32_e32 v38, v188, v38
	v_cvt_pk_bf16_f32 v37, v37, v38
	v_mul_f32_e32 v38, v32, v210
	v_mul_f32_e32 v39, v33, v211
	v_mul_f32_e32 v32, v32, v211
	v_mul_f32_e32 v33, v33, v210
	v_sub_f32_e32 v38, v38, v39
	v_add_f32_e32 v32, v32, v33
	v_mul_f32_e32 v38, v188, v38
	v_mul_f32_e32 v32, v188, v32
	v_cvt_pk_bf16_f32 v38, v38, v32
	v_mul_f32_e32 v32, v34, v212
	v_mul_f32_e32 v33, v35, v213
	v_mov_b32_e32 v40, 1.0
	v_sub_f32_e32 v32, v32, v33
	v_mul_f32_e32 v39, v188, v32
	v_mul_f32_e32 v32, v34, v213
	v_mul_f32_e32 v33, v35, v212
	v_mov_b32_e32 v34, 1.0
	v_add_f32_e32 v32, v32, v33
	v_mul_f32_e32 v32, v188, v32
	v_cvt_pk_bf16_f32 v39, v39, v32
	global_store_dwordx4 v[52:53], v[36:39], off offset:256
	v_mov_b32_e32 v33, 0
	v_mov_b32_e32 v32, 1.0
	v_mov_b32_e32 v35, 0
	v_mov_b32_e32 v36, 1.0
	v_mov_b32_e32 v37, 0
	v_mov_b32_e32 v38, 1.0
	v_mov_b32_e32 v39, 0
	v_mov_b32_e32 v41, 0
	s_nop 1
; __device__ __forceinline__ unsigned cvt_pk_bf16(float lo, float hi) { unsigned r; asm volatile("v_cvt_pk_bf16_f32 %0, %1, %2" : "=v"(r) : "v"(lo), "v"(hi)); return r; }
; #define PG8_BAR __builtin_amdgcn_s_barrier()
;     __device__ __forceinline__ void operator()(const f32x4 (&acc)[2][2][4][2], const Unit& u, int wr, int wc, int fr, int fq) const {
;     ...
;             for (int m = 0; m < 4; ++m) { const int r = rl + ai * HALF + m * 16; bf16_t* rowp = O + (size_t)(u.pm * BM + r) * ldc + col0;
;                 f32x4 t0 = (f32x4){1.f, 0.f, 1.f, 0.f}, t1 = t0;
;                 if (dorope) { const int pos = tt * 256 - 256 + r; const int pp = (i0 < 16) ? (pos >> 6) : (pos & 63); const f32x4* tb = (const f32x4*)(rope + (pp * 16 + (i0 & 15)) * 2); t0 = tb[0]; t1 = tb[1]; }
; #pragma unroll
;                 for (int bj = 0; bj < 2; ++bj) { const f32x4 v0 = acc[ai][bj][m][0], v1 = acc[ai][bj][m][1]; u32x4 w;
;                     w.x = cvt_pk_bf16((v0[0] * t0[0] - v0[1] * t0[1]) * sc, (v0[0] * t0[1] + v0[1] * t0[0]) * sc);
;                     w.y = cvt_pk_bf16((v0[2] * t0[2] - v0[3] * t0[3]) * sc, (v0[2] * t0[3] + v0[3] * t0[2]) * sc);
;                     w.z = cvt_pk_bf16((v1[0] * t1[0] - v1[1] * t1[1]) * sc, (v1[0] * t1[1] + v1[1] * t1[0]) * sc);
;                     w.w = cvt_pk_bf16((v1[2] * t1[2] - v1[3] * t1[3]) * sc, (v1[2] * t1[3] + v1[3] * t1[2]) * sc);
;                     *(u32x4*)(rowp + bj * HALF) = w; } }
; template <class Epi, class Sched, bool ALIGN_EPI = false, bool SP2 = false>
; __device__ __forceinline__ void gemm_phase(PG8_LAS unsigned char* lds, const Gemm g, const Sched& S, const Epi& E) {
;     ...
;         if constexpr (ALIGN_EPI) { if (wr == 0) PG8_BAR; }
;         if constexpr (!Epi::AFTER_DRAIN) { E(acc, cur, wr, wc, fr, fq); S.done(cur); }
;         if (!has_next) break;
; #pragma unroll
;         for (int a = 0; a < 2; ++a)
; #pragma unroll
;             for (int b = 0; b < 2; ++b)
; #pragma unroll
;                 for (int m = 0; m < 4; ++m)
; #pragma unroll
;                     for (int n = 0; n < 2; ++n) acc[a][b][m][n] = (f32x4){0.f, 0.f, 0.f, 0.f};
;         cur = nxt; cA = nA; cB = nB; ++ui;
;         if constexpr (ALIGN_EPI) { if (wr == 1) PG8_BAR; }
.LBB0_1047:
	v_add_u32_e32 v44, s55, v168
	v_mov_b64_e32 v[42:43], s[44:45]
	v_mad_i64_i32 v[42:43], s[66:67], v44, s79, v[42:43]
	s_waitcnt vmcnt(6)
	v_mul_f32_e32 v44, v28, v198
	v_mul_f32_e32 v45, v29, v199
	v_mul_f32_e32 v28, v28, v199
	v_mul_f32_e32 v29, v29, v198
	v_sub_f32_e32 v44, v44, v45
	v_add_f32_e32 v28, v28, v29
	v_mul_f32_e32 v44, v188, v44
	v_mul_f32_e32 v28, v188, v28
	v_cvt_pk_bf16_f32 v28, v44, v28
	v_mul_f32_e32 v44, v30, v200
	v_mul_f32_e32 v45, v31, v201
	v_mul_f32_e32 v30, v30, v201
	v_mul_f32_e32 v31, v31, v200
	v_sub_f32_e32 v29, v44, v45
	v_add_f32_e32 v30, v30, v31
	v_mul_f32_e32 v29, v188, v29
	v_mul_f32_e32 v30, v188, v30
	v_cvt_pk_bf16_f32 v29, v29, v30
	v_mul_f32_e32 v30, v24, v194
	v_mul_f32_e32 v31, v25, v195
	v_mul_f32_e32 v24, v24, v195
	v_mul_f32_e32 v25, v25, v194
	v_sub_f32_e32 v30, v30, v31
	v_add_f32_e32 v24, v24, v25
	v_mul_f32_e32 v30, v188, v30
	v_mul_f32_e32 v24, v188, v24
	v_cvt_pk_bf16_f32 v30, v30, v24
	v_mul_f32_e32 v24, v26, v196
	v_mul_f32_e32 v25, v27, v197
	v_lshl_add_u64 v[42:43], v[154:155], 1, v[42:43]
	v_sub_f32_e32 v24, v24, v25
	v_mul_f32_e32 v31, v188, v24
	v_mul_f32_e32 v24, v26, v197
	v_mul_f32_e32 v25, v27, v196
	s_and_b64 vcc, exec, s[10:11]
	v_add_f32_e32 v24, v24, v25
	v_mul_f32_e32 v24, v188, v24
	v_cvt_pk_bf16_f32 v31, v31, v24
	v_mul_f32_e32 v24, v20, v198
	v_mul_f32_e32 v25, v21, v199
	v_mul_f32_e32 v20, v20, v199
	v_mul_f32_e32 v21, v21, v198
	v_sub_f32_e32 v24, v24, v25
	v_add_f32_e32 v20, v20, v21
	v_mul_f32_e32 v24, v188, v24
	v_mul_f32_e32 v20, v188, v20
	global_store_dwordx4 v[42:43], v[28:31], off
	v_cvt_pk_bf16_f32 v20, v24, v20
	v_mul_f32_e32 v24, v22, v200
	v_mul_f32_e32 v25, v23, v201
	v_mul_f32_e32 v22, v22, v201
	v_mul_f32_e32 v23, v23, v200
	v_sub_f32_e32 v21, v24, v25
	v_add_f32_e32 v22, v22, v23
	v_mul_f32_e32 v21, v188, v21
	v_mul_f32_e32 v22, v188, v22
	v_cvt_pk_bf16_f32 v21, v21, v22
	v_mul_f32_e32 v22, v16, v194
	v_mul_f32_e32 v23, v17, v195
	v_mul_f32_e32 v16, v16, v195
	v_mul_f32_e32 v17, v17, v194
	v_sub_f32_e32 v22, v22, v23
	v_add_f32_e32 v16, v16, v17
	v_mul_f32_e32 v22, v188, v22
	v_mul_f32_e32 v16, v188, v16
	v_cvt_pk_bf16_f32 v22, v22, v16
	v_mul_f32_e32 v16, v18, v196
	v_mul_f32_e32 v17, v19, v197
	v_mov_b32_e32 v34, 1.0
	v_sub_f32_e32 v16, v16, v17
	v_mul_f32_e32 v23, v188, v16
	v_mul_f32_e32 v16, v18, v197
	v_mul_f32_e32 v17, v19, v196
	v_mov_b32_e32 v35, 0
	v_add_f32_e32 v16, v16, v17
	v_mul_f32_e32 v16, v188, v16
	v_cvt_pk_bf16_f32 v23, v23, v16
	v_mov_b32_e32 v16, 1.0
	v_mov_b32_e32 v17, 0
	v_mov_b32_e32 v18, 1.0
	v_mov_b32_e32 v19, 0
	global_store_dwordx4 v[42:43], v[20:23], off offset:256
	s_nop 1
.LBB0_1049:
	s_nop 0
	v_add_u32_e32 v22, s55, v169
	v_mov_b64_e32 v[20:21], s[44:45]
	v_mad_i64_i32 v[20:21], s[10:11], v22, s79, v[20:21]
	s_waitcnt vmcnt(4)
	v_mul_f32_e32 v22, v12, v206
	v_mul_f32_e32 v23, v13, v207
	v_mul_f32_e32 v12, v12, v207
	v_mul_f32_e32 v13, v13, v206
	v_sub_f32_e32 v22, v22, v23
	v_add_f32_e32 v12, v12, v13
	v_mul_f32_e32 v22, v188, v22
	v_mul_f32_e32 v12, v188, v12
	v_cvt_pk_bf16_f32 v12, v22, v12
	v_mul_f32_e32 v22, v14, v208
	v_mul_f32_e32 v23, v15, v209
	v_mul_f32_e32 v14, v14, v209
	v_mul_f32_e32 v15, v15, v208
	v_sub_f32_e32 v13, v22, v23
	v_add_f32_e32 v14, v14, v15
	v_mul_f32_e32 v13, v188, v13
	v_mul_f32_e32 v14, v188, v14
	v_cvt_pk_bf16_f32 v13, v13, v14
	v_mul_f32_e32 v14, v8, v202
	v_mul_f32_e32 v15, v9, v203
	v_mul_f32_e32 v8, v8, v203
	v_mul_f32_e32 v9, v9, v202
	v_sub_f32_e32 v14, v14, v15
	v_add_f32_e32 v8, v8, v9
	v_mul_f32_e32 v14, v188, v14
	v_mul_f32_e32 v8, v188, v8
	v_cvt_pk_bf16_f32 v14, v14, v8
	v_mul_f32_e32 v8, v10, v204
	v_mul_f32_e32 v9, v11, v205
	v_lshl_add_u64 v[20:21], v[154:155], 1, v[20:21]
	v_sub_f32_e32 v8, v8, v9
	v_mul_f32_e32 v15, v188, v8
	v_mul_f32_e32 v8, v10, v205
	v_mul_f32_e32 v9, v11, v204
	s_andn2_b64 vcc, exec, s[8:9]
	v_add_f32_e32 v8, v8, v9
	v_mul_f32_e32 v8, v188, v8
	v_cvt_pk_bf16_f32 v15, v15, v8
	v_mul_f32_e32 v8, v4, v206
	v_mul_f32_e32 v9, v5, v207
	v_mul_f32_e32 v4, v4, v207
	v_mul_f32_e32 v5, v5, v206
	v_sub_f32_e32 v8, v8, v9
	v_add_f32_e32 v4, v4, v5
	v_mul_f32_e32 v8, v188, v8
	v_mul_f32_e32 v4, v188, v4
	global_store_dwordx4 v[20:21], v[12:15], off
	v_cvt_pk_bf16_f32 v4, v8, v4
	v_mul_f32_e32 v8, v6, v208
	v_mul_f32_e32 v9, v7, v209
	v_mul_f32_e32 v6, v6, v209
	v_mul_f32_e32 v7, v7, v208
	v_sub_f32_e32 v5, v8, v9
	v_add_f32_e32 v6, v6, v7
	v_mul_f32_e32 v5, v188, v5
	v_mul_f32_e32 v6, v188, v6
	v_cvt_pk_bf16_f32 v5, v5, v6
	v_mul_f32_e32 v6, v0, v202
	v_mul_f32_e32 v7, v1, v203
	v_mul_f32_e32 v0, v0, v203
	v_mul_f32_e32 v1, v1, v202
	v_sub_f32_e32 v6, v6, v7
	v_add_f32_e32 v0, v0, v1
	v_mul_f32_e32 v6, v188, v6
	v_mul_f32_e32 v0, v188, v0
	v_cvt_pk_bf16_f32 v6, v6, v0
	v_mul_f32_e32 v0, v2, v204
	v_mul_f32_e32 v1, v3, v205
	s_mov_b64 s[8:9], -1
	v_sub_f32_e32 v0, v0, v1
	v_mul_f32_e32 v7, v188, v0
	v_mul_f32_e32 v0, v2, v205
	v_mul_f32_e32 v1, v3, v204
	s_nop 0
	v_add_f32_e32 v0, v0, v1
	v_mul_f32_e32 v0, v188, v0
	v_cvt_pk_bf16_f32 v7, v7, v0
	global_store_dwordx4 v[20:21], v[4:7], off offset:256
	s_cbranch_vccnz .LBB0_1026
	s_andn2_b64 vcc, exec, s[36:37]
	s_cbranch_vccnz .LBB0_1025
	s_barrier
	s_branch .LBB0_1025
